# v006 + attention: SLP-packed v_pk_mul/add/fma_f32 beside MFMAs split into scalar pairs (instruction selection lever)
# baseline (speedup 1.0000x reference)
; template <int MODE  , int QLO, int QHI> ...
;     ...
;         float tmax[4];
; #pragma unroll
;         for (int qt = QLO; qt < QHI; ++qt) {
;             const float a = fmaxf(fmaxf(fmaxf(sA[qt][0], sA[qt][1]), fmaxf(sA[qt][2], sA[qt][3])), fmaxf(fmaxf(sB[qt][0], sB[qt][1]), fmaxf(sB[qt][2], sB[qt][3])));
;             tmax[qt] = xmax16_32(a);
;         }
;         bool need = false;
; #pragma unroll
;         for (int qt = QLO; qt < QHI; ++qt) need = need || (tmax[qt] > mrun[qt] + 8.f);
;         if (__builtin_amdgcn_ballot_w64(need) != 0ull) {
; #pragma unroll
;             for (int qt = QLO; qt < QHI; ++qt) {
;                 const float mnew = fmaxf(mrun[qt], tmax[qt]); const float alpha = __builtin_amdgcn_exp2f(mrun[qt] - mnew);
;                 mrun[qt] = mnew; lrun[qt] *= alpha;
; #pragma unroll
;                 for (int dt = 0; dt < 4; ++dt) O[qt][dt] = O[qt][dt] * alpha;
;             }
;         }
.LBB0_587:
	v_max3_f32 v161, v156, v157, v158
	v_max3_f32 v195, v159, v152, v153
	v_max3_f32 v161, v161, v154, v155
	v_max_f32_e32 v197, v161, v195
	v_max3_f32 v161, v148, v149, v150
	v_max3_f32 v195, v151, v144, v145
	v_max3_f32 v161, v161, v146, v147
	v_max_f32_e32 v196, v161, v195
	v_max3_f32 v161, v140, v141, v142
	v_max3_f32 v195, v143, v136, v137
	v_max3_f32 v161, v161, v138, v139
	v_max_f32_e32 v195, v161, v195
	v_max3_f32 v161, v128, v129, v130
	v_max3_f32 v198, v131, v132, v133
	v_max3_f32 v161, v161, v134, v135
	v_max_f32_e32 v161, v161, v198
	v_add_f32_e32 v198, 0x41000000, v194
	v_cmp_gt_f32_e32 vcc, v197, v198
	v_add_f32_e32 v198, 0x41000000, v193
	v_cmp_gt_f32_e64 s[0:1], v196, v198
	v_add_f32_e32 v198, 0x41000000, v192
	s_or_b64 s[0:1], vcc, s[0:1]
	v_cmp_gt_f32_e32 vcc, v195, v198
	v_add_f32_e32 v198, 0x41000000, v167
	s_or_b64 s[0:1], s[0:1], vcc
	v_cmp_gt_f32_e32 vcc, v161, v198
	s_or_b64 vcc, s[0:1], vcc
	s_cbranch_vccz .LBB0_589
	v_mov_b32_e32 v198, v197
	s_nop 1
	v_permlane16_swap_b32_e32 v197, v198
	v_max_f32_e32 v197, v197, v198
	v_mov_b32_e32 v198, v197
	s_nop 1
	v_permlane32_swap_b32_e32 v197, v198
	v_max_f32_e32 v197, v197, v198
	v_mov_b32_e32 v198, v196
	s_nop 1
	v_permlane16_swap_b32_e32 v196, v198
	v_max_f32_e32 v196, v196, v198
	v_mov_b32_e32 v198, v196
	s_nop 1
	v_permlane32_swap_b32_e32 v196, v198
	v_max_f32_e32 v196, v196, v198
	v_mov_b32_e32 v198, v195
	s_nop 1
	v_permlane16_swap_b32_e32 v195, v198
	v_max_f32_e32 v195, v195, v198
	v_mov_b32_e32 v198, v195
	s_nop 1
	v_permlane32_swap_b32_e32 v195, v198
	v_max_f32_e32 v195, v195, v198
	v_mov_b32_e32 v198, v161
	s_nop 1
	v_permlane16_swap_b32_e32 v161, v198
	v_max_f32_e32 v161, v161, v198
	v_mov_b32_e32 v198, v161
	s_nop 1
	v_permlane32_swap_b32_e32 v161, v198
	v_max_f32_e32 v161, v161, v198
	v_max_f32_e32 v197, v197, v197
	v_max_f32_e32 v198, v194, v194
	v_max_f32_e32 v197, v198, v197
	v_sub_f32_e32 v194, v194, v197
	v_exp_f32_e32 v198, v194
	v_max_f32_e32 v194, v196, v196
	v_max_f32_e32 v196, v193, v193
	v_max_f32_e32 v196, v196, v194
	v_sub_f32_e32 v193, v193, v196
	v_pk_mul_f32 v[62:63], v[62:63], v[198:199] op_sel_hi:[1,0]
	v_pk_mul_f32 v[60:61], v[60:61], v[198:199] op_sel_hi:[1,0]
	v_pk_mul_f32 v[58:59], v[58:59], v[198:199] op_sel_hi:[1,0]
	v_pk_mul_f32 v[56:57], v[56:57], v[198:199] op_sel_hi:[1,0]
	v_pk_mul_f32 v[54:55], v[54:55], v[198:199] op_sel_hi:[1,0]
	v_pk_mul_f32 v[52:53], v[52:53], v[198:199] op_sel_hi:[1,0]
	v_pk_mul_f32 v[50:51], v[50:51], v[198:199] op_sel_hi:[1,0]
	v_pk_mul_f32 v[48:49], v[48:49], v[198:199] op_sel_hi:[1,0]
	v_exp_f32_e32 v199, v193
	v_max_f32_e32 v193, v195, v195
	v_max_f32_e32 v161, v161, v161
	v_mov_b32_e32 v194, v199
	v_pk_mul_f32 v[46:47], v[46:47], v[194:195] op_sel_hi:[1,0]
	v_pk_mul_f32 v[44:45], v[44:45], v[194:195] op_sel_hi:[1,0]
	v_max_f32_e32 v195, v192, v192
	v_max_f32_e32 v195, v195, v193
	v_sub_f32_e32 v192, v192, v195
	v_exp_f32_e32 v192, v192
	v_mul_f32_e32 v178, v178, v198
	v_mul_f32_e32 v179, v179, v199
	v_pk_mul_f32 v[42:43], v[42:43], v[194:195] op_sel_hi:[1,0]
	v_pk_mul_f32 v[40:41], v[40:41], v[194:195] op_sel_hi:[1,0]
	v_pk_mul_f32 v[30:31], v[30:31], v[192:193] op_sel_hi:[1,0]
	v_pk_mul_f32 v[28:29], v[28:29], v[192:193] op_sel_hi:[1,0]
	v_pk_mul_f32 v[26:27], v[26:27], v[192:193] op_sel_hi:[1,0]
	v_pk_mul_f32 v[24:25], v[24:25], v[192:193] op_sel_hi:[1,0]
	v_pk_mul_f32 v[22:23], v[22:23], v[192:193] op_sel_hi:[1,0]
	v_pk_mul_f32 v[20:21], v[20:21], v[192:193] op_sel_hi:[1,0]
	v_pk_mul_f32 v[18:19], v[18:19], v[192:193] op_sel_hi:[1,0]
	v_pk_mul_f32 v[16:17], v[16:17], v[192:193] op_sel_hi:[1,0]
	v_max_f32_e32 v193, v167, v167
	v_max_f32_e32 v161, v193, v161
	v_sub_f32_e32 v167, v167, v161
	v_exp_f32_e32 v193, v167
	v_pk_mul_f32 v[38:39], v[38:39], v[194:195] op_sel_hi:[1,0]
	v_pk_mul_f32 v[36:37], v[36:37], v[194:195] op_sel_hi:[1,0]
	v_pk_mul_f32 v[34:35], v[34:35], v[194:195] op_sel_hi:[1,0]
	v_mul_f32_e32 v170, v170, v192
	v_mul_f32_e32 v171, v171, v193
	v_mov_b32_e32 v192, v193
	v_pk_mul_f32 v[32:33], v[32:33], v[194:195] op_sel_hi:[1,0]
	v_pk_mul_f32 v[14:15], v[14:15], v[192:193] op_sel_hi:[1,0]
	v_pk_mul_f32 v[12:13], v[12:13], v[192:193] op_sel_hi:[1,0]
	v_pk_mul_f32 v[10:11], v[10:11], v[192:193] op_sel_hi:[1,0]
	v_pk_mul_f32 v[8:9], v[8:9], v[192:193] op_sel_hi:[1,0]
	v_pk_mul_f32 v[6:7], v[6:7], v[192:193] op_sel_hi:[1,0]
	v_pk_mul_f32 v[4:5], v[4:5], v[192:193] op_sel_hi:[1,0]
	v_pk_mul_f32 v[2:3], v[2:3], v[192:193] op_sel_hi:[1,0]
	v_pk_mul_f32 v[0:1], v[0:1], v[192:193] op_sel_hi:[1,0]
	v_mov_b32_e32 v167, v161
	v_mov_b32_e32 v192, v195
	v_mov_b32_e32 v193, v196
	v_mov_b32_e32 v194, v197
; __device__ __forceinline__ u32x4 pack8(f32x4 a, f32x4 b) { u32x4 w; w.x = cvt_pk_bf16(a[0], a[1]); w.y = cvt_pk_bf16(a[2], a[3]); w.z = cvt_pk_bf16(b[0], b[1]); w.w = cvt_pk_bf16(b[2], b[3]); return w; }
; template <int MODE  , int QLO, int QHI> ...
;     ...
; #pragma unroll
;         for (int qt = QLO; qt < QHI; ++qt) {
;             const int TA = jtA - (j0 + 16 * qt), TB = TA + 16;
;             const bool rA = vA && (same ? (TA >= -256 && TA <= 256) : (TA >= -16 && TA <= 16));
;             const bool rB = vB && (same ? (TB >= -256 && TB <= 256) : (TB >= -16 && TB <= 16));
;             const int ixA = same ? ((TA + 256) >> 4) : (33 + (dr + 3) * 3 + ((TA + 16) >> 4));
;             const f32x4 cAq = ctf[(rA ? ixA : 54) * 64 + lane], cBq = ctf[(rB ? ixA + 1 : 54) * 64 + lane];
;             const f32x4 dA = sA[qt] - mrun[qt], dB = sB[qt] - mrun[qt];
;             f32x4 eA, eB;
; #pragma unroll
;             for (int r = 0; r < 4; ++r) { eA[r] = __builtin_amdgcn_exp2f(dA[r]); eB[r] = __builtin_amdgcn_exp2f(dB[r]); }
;             const f32x4 pA = cAq * eA, pB = cBq * eB;
;             const f32x4 sm = pA + pB;
;             lrun[qt] += (sm[0] + sm[1]) + (sm[2] + sm[3]);
;             const bf16x8 P = __builtin_bit_cast(bf16x8, pg8::pack8(pA, pB));
; #pragma unroll
;             for (int dt = 0; dt < 4; ++dt) O[qt][dt] = __builtin_amdgcn_mfma_f32_16x16x32_bf16(Vf[dt], P, O[qt][dt], 0, 0, 0);
;         }
.LBB0_589:
	s_cmp_lt_i32 s33, 4
	s_cselect_b32 s0, 8, 2
	s_add_i32 s5, s0, s33
	s_lshl_b32 s4, s5, 5
	s_add_i32 s0, s4, s80
	s_cmpk_lt_u32 s0, 0x800
	s_cselect_b64 s[0:1], -1, 0
	s_xor_b32 s83, s83, 1
	s_cmpk_lt_u32 s4, 0x201
	s_cselect_b64 s[14:15], -1, 0
	s_and_b64 s[14:15], s[14:15], s[0:1]
	s_or_b32 s33, s4, 16
	s_cmpk_lt_u32 s33, 0x201
	s_cselect_b64 s[42:43], -1, 0
	s_and_b64 s[42:43], s[0:1], s[42:43]
	s_lshl_b32 s5, s5, 7
	s_and_b64 s[14:15], s[14:15], exec
	s_cselect_b32 s14, s5, 0xd80
	s_or_b32 s33, s5, 64
	v_lshl_add_u32 v161, s14, 4, v188
	s_and_b64 s[14:15], s[42:43], exec
	v_sub_f32_e32 v156, v156, v194
	s_cselect_b32 s14, s33, 0xd80
	v_exp_f32_e32 v204, v156
	v_sub_f32_e32 v156, v157, v194
	v_lshl_add_u32 v195, s14, 4, v188
	v_exp_f32_e32 v205, v156
	v_sub_f32_e32 v156, v158, v194
	s_add_i32 s14, s4, -16
	ds_read_b128 v[196:199], v161
	ds_read_b128 v[200:203], v195
	v_sub_f32_e32 v152, v152, v194
	v_sub_f32_e32 v153, v153, v194
	v_exp_f32_e32 v208, v156
	v_sub_f32_e32 v154, v154, v194
	v_sub_f32_e32 v156, v159, v194
	v_sub_f32_e32 v155, v155, v194
	s_cmpk_lt_u32 s14, 0x201
	v_exp_f32_e32 v152, v152
	v_exp_f32_e32 v153, v153
	v_exp_f32_e32 v209, v156
	v_exp_f32_e32 v154, v154
	v_exp_f32_e32 v155, v155
	s_cselect_b64 s[14:15], -1, 0
	s_and_b64 s[14:15], s[0:1], s[14:15]
	s_sub_i32 s33, s5, 64
	s_and_b64 s[14:15], s[14:15], exec
	s_cselect_b32 s14, s33, 0xd80
	s_waitcnt lgkmcnt(1)
	v_mul_f32_e32 v156, v198, v208
	v_mul_f32_e32 v157, v199, v209
	v_mul_f32_e32 v158, v196, v204
	v_mul_f32_e32 v159, v197, v205
	s_waitcnt lgkmcnt(0)
	v_mul_f32_e32 v200, v200, v152
	v_mul_f32_e32 v201, v201, v153
	v_mul_f32_e32 v202, v202, v154
	v_mul_f32_e32 v203, v203, v155
	v_cvt_pk_bf16_f32 v152, v158, v159
	v_cvt_pk_bf16_f32 v153, v156, v157
	v_cvt_pk_bf16_f32 v154, v200, v201
	v_lshl_add_u32 v195, s14, 4, v188
	v_cvt_pk_bf16_f32 v155, v202, v203
	s_sub_i32 s14, s4, 32
	v_mfma_f32_16x16x32_bf16 v[60:63], v[124:127], v[152:155], v[60:63]
	v_sub_f32_e32 v148, v148, v193
	v_sub_f32_e32 v144, v144, v193
	v_sub_f32_e32 v149, v149, v193
	v_mfma_f32_16x16x32_bf16 v[56:59], v[120:123], v[152:155], v[56:59]
	v_sub_f32_e32 v145, v145, v193
	v_sub_f32_e32 v150, v150, v193
	v_sub_f32_e32 v146, v146, v193
	v_mfma_f32_16x16x32_bf16 v[52:55], v[116:119], v[152:155], v[52:55]
	v_sub_f32_e32 v151, v151, v193
	v_sub_f32_e32 v147, v147, v193
	s_cmpk_lt_u32 s14, 0x201
	v_mfma_f32_16x16x32_bf16 v[48:51], v[112:115], v[152:155], v[48:51]
	ds_read_b128 v[152:155], v195
	ds_read_b128 v[156:159], v161
	v_exp_f32_e32 v148, v148
	v_exp_f32_e32 v144, v144
	v_exp_f32_e32 v149, v149
	v_exp_f32_e32 v145, v145
	v_exp_f32_e32 v150, v150
	v_exp_f32_e32 v151, v151
	v_exp_f32_e32 v146, v146
	v_exp_f32_e32 v147, v147
	s_cselect_b64 s[14:15], -1, 0
	s_and_b64 s[14:15], s[0:1], s[14:15]
	s_add_i32 s33, s5, 0xffffff80
	s_and_b64 s[14:15], s[14:15], exec
	s_cselect_b32 s14, s33, 0xd80
	s_waitcnt lgkmcnt(1)
	v_mul_f32_e32 v210, v150, v154
	v_mul_f32_e32 v211, v151, v155
	v_mul_f32_e32 v212, v148, v152
	v_mul_f32_e32 v213, v149, v153
	s_waitcnt lgkmcnt(0)
	v_mul_f32_e32 v156, v144, v156
	v_mul_f32_e32 v157, v145, v157
	v_mul_f32_e32 v158, v146, v158
	v_mul_f32_e32 v159, v147, v159
	v_cvt_pk_bf16_f32 v144, v212, v213
	v_cvt_pk_bf16_f32 v145, v210, v211
	v_cvt_pk_bf16_f32 v146, v156, v157
	v_lshl_add_u32 v161, s14, 4, v188
	v_cvt_pk_bf16_f32 v147, v158, v159
	v_fma_f32 v154, v150, v154, v158
	v_fma_f32 v155, v151, v155, v159
	v_mfma_f32_16x16x32_bf16 v[44:47], v[124:127], v[144:147], v[44:47]
	v_fma_f32 v152, v148, v152, v156
	v_fma_f32 v153, v149, v153, v157
	v_sub_f32_e32 v140, v140, v192
	v_sub_f32_e32 v136, v136, v192
	v_mfma_f32_16x16x32_bf16 v[40:43], v[120:123], v[144:147], v[40:43]
	v_sub_f32_e32 v141, v141, v192
	v_sub_f32_e32 v137, v137, v192
	s_sub_i32 s4, s4, 48
	v_mfma_f32_16x16x32_bf16 v[36:39], v[116:119], v[144:147], v[36:39]
	v_exp_f32_e32 v140, v140
	v_exp_f32_e32 v136, v136
	v_exp_f32_e32 v141, v141
	v_mfma_f32_16x16x32_bf16 v[32:35], v[112:115], v[144:147], v[32:35]
	ds_read_b128 v[144:147], v161
	ds_read_b128 v[148:151], v195
	v_exp_f32_e32 v137, v137
	v_sub_f32_e32 v142, v142, v192
	v_sub_f32_e32 v138, v138, v192
	v_sub_f32_e32 v143, v143, v192
	v_sub_f32_e32 v139, v139, v192
	s_cmpk_lt_u32 s4, 0x201
	v_exp_f32_e32 v142, v142
	v_exp_f32_e32 v143, v143
	v_exp_f32_e32 v138, v138
	v_exp_f32_e32 v139, v139
	s_cselect_b64 s[14:15], -1, 0
	s_and_b64 s[0:1], s[0:1], s[14:15]
	s_addk_i32 s5, 0xff40
	v_fma_f32 v196, v196, v204, v200
	v_fma_f32 v197, v197, v205, v201
	s_and_b64 s[0:1], s[0:1], exec
	v_mov_b32_e32 v156, v196
	v_mov_b32_e32 v157, v152
	v_mov_b32_e32 v152, v197
	s_waitcnt lgkmcnt(1)
; __device__ __forceinline__ u32x4 pack8(f32x4 a, f32x4 b) { u32x4 w; w.x = cvt_pk_bf16(a[0], a[1]); w.y = cvt_pk_bf16(a[2], a[3]); w.z = cvt_pk_bf16(b[0], b[1]); w.w = cvt_pk_bf16(b[2], b[3]); return w; }
; template <int MODE  , int QLO, int QHI> ...
;     ...
; #pragma unroll
;         for (int qt = QLO; qt < QHI; ++qt) {
;             const int TA = jtA - (j0 + 16 * qt), TB = TA + 16;
;             const bool rA = vA && (same ? (TA >= -256 && TA <= 256) : (TA >= -16 && TA <= 16));
;             const bool rB = vB && (same ? (TB >= -256 && TB <= 256) : (TB >= -16 && TB <= 16));
;             const int ixA = same ? ((TA + 256) >> 4) : (33 + (dr + 3) * 3 + ((TA + 16) >> 4));
;             const f32x4 cAq = ctf[(rA ? ixA : 54) * 64 + lane], cBq = ctf[(rB ? ixA + 1 : 54) * 64 + lane];
;             const f32x4 dA = sA[qt] - mrun[qt], dB = sB[qt] - mrun[qt];
;             f32x4 eA, eB;
; #pragma unroll
;             for (int r = 0; r < 4; ++r) { eA[r] = __builtin_amdgcn_exp2f(dA[r]); eB[r] = __builtin_amdgcn_exp2f(dB[r]); }
;             const f32x4 pA = cAq * eA, pB = cBq * eB;
;             const f32x4 sm = pA + pB;
;             lrun[qt] += (sm[0] + sm[1]) + (sm[2] + sm[3]);
;             const bf16x8 P = __builtin_bit_cast(bf16x8, pg8::pack8(pA, pB));
; #pragma unroll
;             for (int dt = 0; dt < 4; ++dt) O[qt][dt] = __builtin_amdgcn_mfma_f32_16x16x32_bf16(Vf[dt], P, O[qt][dt], 0, 0, 0);
;         }
	v_mul_f32_e32 v196, v140, v144
	v_mul_f32_e32 v197, v141, v145
	s_waitcnt lgkmcnt(0)
	v_mul_f32_e32 v148, v136, v148
	v_mul_f32_e32 v149, v137, v149
	v_cvt_pk_bf16_f32 v136, v196, v197
	s_cselect_b32 s0, s5, 0xd80
	v_mul_f32_e32 v158, v142, v146
	v_mul_f32_e32 v159, v143, v147
	v_mul_f32_e32 v150, v138, v150
	v_mul_f32_e32 v151, v139, v151
	v_cvt_pk_bf16_f32 v137, v158, v159
	v_cvt_pk_bf16_f32 v138, v148, v149
	v_fma_f32 v144, v140, v144, v148
	v_fma_f32 v145, v141, v145, v149
	v_cvt_pk_bf16_f32 v139, v150, v151
	v_fma_f32 v146, v142, v146, v150
	v_fma_f32 v147, v143, v147, v151
	v_mfma_f32_16x16x32_bf16 v[28:31], v[124:127], v[136:139], v[28:31]
	v_sub_f32_e32 v132, v132, v167
	v_sub_f32_e32 v133, v133, v167
	v_sub_f32_e32 v134, v134, v167
	v_mfma_f32_16x16x32_bf16 v[24:27], v[120:123], v[136:139], v[24:27]
	v_sub_f32_e32 v135, v135, v167
	v_sub_f32_e32 v128, v128, v167
	v_exp_f32_e32 v132, v132
	v_mfma_f32_16x16x32_bf16 v[20:23], v[116:119], v[136:139], v[20:23]
	v_sub_f32_e32 v129, v129, v167
	v_exp_f32_e32 v133, v133
	v_sub_f32_e32 v130, v130, v167
	v_mfma_f32_16x16x32_bf16 v[16:19], v[112:115], v[136:139], v[16:19]
	v_lshl_add_u32 v136, s0, 4, v188
	ds_read_b128 v[136:139], v136
	ds_read_b128 v[140:143], v161
	v_sub_f32_e32 v131, v131, v167
	v_exp_f32_e32 v134, v134
	v_exp_f32_e32 v135, v135
	v_exp_f32_e32 v128, v128
	v_exp_f32_e32 v129, v129
	v_exp_f32_e32 v130, v130
	v_exp_f32_e32 v131, v131
	s_waitcnt lgkmcnt(0)
	v_mul_f32_e32 v132, v132, v140
	v_mul_f32_e32 v133, v133, v141
	v_mul_f32_e32 v134, v134, v142
	v_mul_f32_e32 v135, v135, v143
	v_fma_f32 v198, v198, v208, v202
	v_fma_f32 v199, v199, v209, v203
	v_mul_f32_e32 v148, v130, v138
	v_mul_f32_e32 v149, v131, v139
	v_mul_f32_e32 v150, v128, v136
	v_mul_f32_e32 v151, v129, v137
	v_fma_f32 v138, v130, v138, v134
	v_fma_f32 v139, v131, v139, v135
	v_fma_f32 v136, v128, v136, v132
	v_fma_f32 v137, v129, v137, v133
	v_add_f32_e32 v152, v156, v152
	v_add_f32_e32 v153, v157, v153
	v_mov_b32_e32 v156, v198
	v_mov_b32_e32 v157, v154
	v_mov_b32_e32 v154, v199
	v_mov_b32_e32 v140, v144
	v_mov_b32_e32 v141, v136
	v_cvt_pk_bf16_f32 v128, v150, v151
	v_cvt_pk_bf16_f32 v129, v148, v149
	v_cvt_pk_bf16_f32 v130, v132, v133
	v_cvt_pk_bf16_f32 v131, v134, v135
	v_mov_b32_e32 v136, v145
	v_mfma_f32_16x16x32_bf16 v[12:15], v[124:127], v[128:131], v[12:15]
	v_mov_b32_e32 v126, v146
	v_mov_b32_e32 v127, v138
	v_mov_b32_e32 v138, v147
	v_mfma_f32_16x16x32_bf16 v[8:11], v[120:123], v[128:131], v[8:11]
	v_add_f32_e64 v154, v156, v154
	v_add_f32_e64 v155, v157, v155
	v_add_f32_e32 v124, v140, v136
	v_add_f32_e32 v125, v141, v137
	v_add_f32_e32 v120, v126, v138
	v_add_f32_e32 v121, v127, v139
	v_mfma_f32_16x16x32_bf16 v[4:7], v[116:119], v[128:131], v[4:7]
	v_add_f32_e64 v152, v152, v154
	v_add_f32_e64 v153, v153, v155
	v_add_f32_e32 v116, v124, v120
	v_add_f32_e32 v117, v125, v121
	v_add_f32_e32 v178, v178, v152
	v_add_f32_e32 v179, v179, v153
	v_mfma_f32_16x16x32_bf16 v[0:3], v[112:115], v[128:131], v[0:3]
	v_add_f32_e64 v170, v170, v116
	v_add_f32_e64 v171, v171, v117
	s_cmp_gt_i32 s66, 5
	s_cbranch_scc1 .LBB0_591
	s_mov_b32 s33, s66
	s_branch .LBB0_546

; __device__ __forceinline__ u32x4 pack8(f32x4 a, f32x4 b) { u32x4 w; w.x = cvt_pk_bf16(a[0], a[1]); w.y = cvt_pk_bf16(a[2], a[3]); w.z = cvt_pk_bf16(b[0], b[1]); w.w = cvt_pk_bf16(b[2], b[3]); return w; }
; __device__ __forceinline__ void pair_decode(int pi, int r4, int j0, int& rk, int& jtA, bool& same) {
;     ...
;     else { const int q = pi - 18, oc = q / 3; rk = (r4 + 1 + oc) & 3; jtA = j0 - 16 + 32 * (q - 3 * oc); same = false; }
; template <int MODE  , int QLO, int QHI> ...
;     ...
; #pragma unroll
;         for (int qt = QLO; qt < QHI; ++qt) {
;             const int TA = jtA - (j0 + 16 * qt), TB = TA + 16;
;             const bool rA = vA && (same ? (TA >= -256 && TA <= 256) : (TA >= -16 && TA <= 16));
;             const bool rB = vB && (same ? (TB >= -256 && TB <= 256) : (TB >= -16 && TB <= 16));
;             const int ixA = same ? ((TA + 256) >> 4) : (33 + (dr + 3) * 3 + ((TA + 16) >> 4));
;             const f32x4 cAq = ctf[(rA ? ixA : 54) * 64 + lane], cBq = ctf[(rB ? ixA + 1 : 54) * 64 + lane];
;             const f32x4 dA = sA[qt] - mrun[qt], dB = sB[qt] - mrun[qt];
;             f32x4 eA, eB;
; #pragma unroll
;             for (int r = 0; r < 4; ++r) { eA[r] = __builtin_amdgcn_exp2f(dA[r]); eB[r] = __builtin_amdgcn_exp2f(dB[r]); }
;             const f32x4 pA = cAq * eA, pB = cBq * eB;
;             const f32x4 sm = pA + pB;
;             lrun[qt] += (sm[0] + sm[1]) + (sm[2] + sm[3]);
;             const bf16x8 P = __builtin_bit_cast(bf16x8, pg8::pack8(pA, pB));
; #pragma unroll
;             for (int dt = 0; dt < 4; ++dt) O[qt][dt] = __builtin_amdgcn_mfma_f32_16x16x32_bf16(Vf[dt], P, O[qt][dt], 0, 0, 0);
;         }
.LBB0_593:
	s_and_b32 s0, s48, 0xff
	s_mul_hi_u32 s0, s0, 0x55555556
	s_mul_i32 s42, s0, 0xffffffa0
	s_mul_i32 s0, s49, 0xab
	s_lshr_b32 s0, s0, 9
	s_add_i32 s0, s82, s0
	s_and_b32 s0, s0, 3
	s_add_i32 s1, s33, s42
	s_add_i32 s14, s1, 0xfffffe10
	s_xor_b32 s83, s83, 1
	s_sub_i32 s43, s0, s75
	s_addk_i32 s1, 0xfe20
	s_cmpk_lt_u32 s1, 0x800
	s_cselect_b64 s[0:1], -1, 0
	s_cmpk_lt_u32 s14, 0x800
	s_cselect_b64 s[14:15], -1, 0
	s_mul_i32 s43, s43, 3
	s_add_i32 s65, s5, s42
	s_add_i32 s58, s43, 42
	s_add_i32 s70, s65, 0xfffffe10
	s_add_i32 s71, s65, 0xfffffe20
	s_cmp_lt_u32 s71, 33
	s_cselect_b64 s[42:43], -1, 0
	s_and_b64 s[66:67], s[14:15], s[42:43]
	s_addk_i32 s65, 0xfe30
	s_cmp_lt_u32 s65, 33
	s_cselect_b64 s[68:69], -1, 0
	s_lshr_b32 s65, s71, 4
	s_add_i32 s65, s65, s58
	s_and_b64 s[68:69], s[0:1], s[68:69]
	s_lshl_b32 s65, s65, 6
	s_and_b64 s[66:67], s[66:67], exec
	s_cselect_b32 s66, s65, 0xd80
	s_add_i32 s65, s65, 64
	v_lshl_add_u32 v144, s66, 4, v188
	s_and_b64 s[66:67], s[68:69], exec
	s_cselect_b32 s65, s65, 0xd80
	s_cmp_lt_u32 s70, 33
	v_lshl_add_u32 v148, s65, 4, v188
	v_sub_f32_e32 v136, v136, v194
	v_sub_f32_e32 v137, v137, v194
	v_sub_f32_e32 v138, v138, v194
	v_sub_f32_e32 v139, v139, v194
	s_cselect_b64 s[66:67], -1, 0
	s_and_b64 s[0:1], s[0:1], s[42:43]
	s_lshr_b32 s42, s70, 4
	ds_read_b128 v[144:147], v144
	ds_read_b128 v[148:151], v148
	v_exp_f32_e32 v152, v136
	v_sub_f32_e32 v136, v140, v194
	v_exp_f32_e32 v153, v137
	v_sub_f32_e32 v137, v141, v194
	v_exp_f32_e32 v140, v138
	v_sub_f32_e32 v138, v142, v194
	v_exp_f32_e32 v141, v139
	v_sub_f32_e32 v139, v143, v194
	s_add_i32 s42, s42, s58
	v_exp_f32_e32 v136, v136
	v_exp_f32_e32 v138, v138
	v_exp_f32_e32 v139, v139
	v_exp_f32_e32 v137, v137
	s_and_b64 s[14:15], s[14:15], s[66:67]
	s_lshl_b32 s42, s42, 6
	s_and_b64 s[14:15], s[14:15], exec
	s_cselect_b32 s14, s42, 0xd80
	s_add_i32 s42, s42, 64
	s_and_b64 s[0:1], s[0:1], exec
	s_waitcnt lgkmcnt(1)
	v_mul_f32_e32 v154, v144, v152
	v_mul_f32_e32 v155, v145, v153
	s_waitcnt lgkmcnt(0)
	v_mul_f32_e32 v150, v150, v138
	v_mul_f32_e32 v151, v151, v139
	v_mul_f32_e32 v148, v148, v136
	v_mul_f32_e32 v149, v149, v137
	v_cvt_pk_bf16_f32 v136, v154, v155
	s_cselect_b32 s0, s42, 0xd80
	v_mul_f32_e32 v142, v146, v140
	v_mul_f32_e32 v143, v147, v141
	v_fma_f32 v146, v146, v140, v150
	v_fma_f32 v147, v147, v141, v151
	v_cvt_pk_bf16_f32 v137, v142, v143
	v_cvt_pk_bf16_f32 v138, v148, v149
	v_cvt_pk_bf16_f32 v139, v150, v151
	v_lshl_add_u32 v140, s0, 4, v188
	v_mfma_f32_16x16x32_bf16 v[60:63], v[124:127], v[136:139], v[60:63]
	v_sub_f32_e32 v132, v132, v193
	v_sub_f32_e32 v133, v133, v193
	v_sub_f32_e32 v128, v128, v193
	v_mfma_f32_16x16x32_bf16 v[56:59], v[120:123], v[136:139], v[56:59]
	v_exp_f32_e32 v132, v132
	v_sub_f32_e32 v129, v129, v193
	v_sub_f32_e32 v134, v134, v193
	v_mfma_f32_16x16x32_bf16 v[52:55], v[116:119], v[136:139], v[52:55]
	v_sub_f32_e32 v135, v135, v193
	v_exp_f32_e32 v133, v133
	v_exp_f32_e32 v128, v128
	v_mfma_f32_16x16x32_bf16 v[48:51], v[112:115], v[136:139], v[48:51]
	v_lshl_add_u32 v136, s14, 4, v188
	ds_read_b128 v[136:139], v136
	ds_read_b128 v[140:143], v140
	v_exp_f32_e32 v129, v129
	v_sub_f32_e32 v130, v130, v193
	v_exp_f32_e32 v134, v134
	v_sub_f32_e32 v131, v131, v193
	v_exp_f32_e32 v135, v135
	v_exp_f32_e32 v130, v130
	v_exp_f32_e32 v131, v131
	s_waitcnt lgkmcnt(0)
	v_mul_f32_e32 v132, v132, v140
	v_mul_f32_e32 v133, v133, v141
	v_fma_f32 v144, v144, v152, v148
	v_fma_f32 v145, v145, v153, v149
	v_mul_f32_e32 v150, v128, v136
	v_mul_f32_e32 v151, v129, v137
	v_mul_f32_e32 v134, v134, v142
	v_mul_f32_e32 v135, v135, v143
	v_fma_f32 v128, v128, v136, v132
	v_fma_f32 v129, v129, v137, v133
	v_mul_f32_e32 v148, v130, v138
	v_mul_f32_e32 v149, v131, v139
	v_fma_f32 v138, v130, v138, v134
	v_fma_f32 v139, v131, v139, v135
	v_mov_b32_e32 v130, v144
	v_mov_b32_e32 v131, v128
	v_mov_b32_e32 v128, v145
	v_add_f32_e32 v136, v130, v128
	v_add_f32_e32 v137, v131, v129
	v_cvt_pk_bf16_f32 v128, v150, v151
	v_cvt_pk_bf16_f32 v129, v148, v149
	v_cvt_pk_bf16_f32 v130, v132, v133
	v_cvt_pk_bf16_f32 v131, v134, v135
	s_add_i32 s4, s4, 1
	v_mfma_f32_16x16x32_bf16 v[44:47], v[124:127], v[128:131], v[44:47]
	v_mov_b32_e32 v124, v146
	v_mov_b32_e32 v125, v138
	v_mov_b32_e32 v138, v147
	v_mfma_f32_16x16x32_bf16 v[40:43], v[120:123], v[128:131], v[40:43]
	v_add_f32_e64 v120, v124, v138
	v_add_f32_e64 v121, v125, v139
	s_addk_i32 s33, 0x60
	v_add_f32_e32 v120, v136, v120
	v_add_f32_e32 v121, v137, v121
	v_mfma_f32_16x16x32_bf16 v[36:39], v[116:119], v[128:131], v[36:39]
	s_add_i32 s48, s48, 3
	s_addk_i32 s5, 0x60
	s_add_i32 s49, s49, 3
	v_mfma_f32_16x16x32_bf16 v[32:35], v[112:115], v[128:131], v[32:35]
	v_add_f32_e64 v178, v178, v120
	v_add_f32_e64 v179, v179, v121
	s_cmp_gt_i32 s4, 7
	s_cbranch_scc1 .LBB0_601
; template <int MODE  , int QLO, int QHI> ...
;     ...
;         float tmax[4];
; #pragma unroll
;         for (int qt = QLO; qt < QHI; ++qt) {
;             const float a = fmaxf(fmaxf(fmaxf(sA[qt][0], sA[qt][1]), fmaxf(sA[qt][2], sA[qt][3])), fmaxf(fmaxf(sB[qt][0], sB[qt][1]), fmaxf(sB[qt][2], sB[qt][3])));
; template <int MODE, int DRY, int QLO, int QHI>
; __device__ __forceinline__ int attn_step(int o, int& par, const AttnCtx& C, const AttnLane& L, f32x4 (&O)[4][4], float (&mrun)[4], float (&lrun)[4], const bf16x8 (&Qf)[4][2], bf16x8 (&Kn)[4]) {
;     ...
;     int rk, jtA; bool same; pair_decode(pi, C.r4, C.j0, rk, jtA, same);
;     const int jtB = jtA + 16;
;     const bool vA = (jtA >= 0) && (jtA < 2048), vB = (jtB >= 0) && (jtB < 2048);
;     const int dr = rk - C.r4;
;     int on = o + 1; while (on < 27 && !pair_valid(order_pair(on), C.r4, C.j0)) ++on;
;     const int pn = order_pair(on < 27 ? on : 0);
;     asm volatile("s_waitcnt vmcnt(0)" ::: "memory");
;     bf16x8 Vf[4];
;     { LAS const unsigned char* vb = C.vl + par * 4096 + (4 * fq + (fr >> 2)) * 64 + (fr & 3) * 8;
; #pragma unroll
;       for (int dt = 0; dt < 4; ++dt) { const s16x4 lo = vtr(vb + (dt >> 1) * 1024 + (dt & 1) * 32), hi = vtr(vb + 2048 + (dt >> 1) * 1024 + (dt & 1) * 32);
;           Vf[dt] = (bf16x8){lo[0], lo[1], lo[2], lo[3], hi[0], hi[1], hi[2], hi[3]}; }
;       asm volatile("" ::: "memory"); }
;     if (DRY != 2) if (on < 27) attn_dma_v(pn, C.r4, C.j0, C.rowbase, C.h, C.vlo, C.Vr, C.vl + (par ^ 1) * 4096);
;     par ^= 1;
;     if (DRY == 1) {
;         asm volatile("" :: "v"(Kn[0]), "v"(Kn[1]), "v"(Kn[2]), "v"(Kn[3]), "v"(Vf[0]), "v"(Vf[1]), "v"(Vf[2]), "v"(Vf[3]));
;         if (on < 27) attn_load_k(pn, C.r4, C.j0, C.rowbase, C.h, C.klo, C.Kr, Kn);
;         return on;
;     }
;     f32x4 sA[4], sB[4];
; #pragma unroll
;     for (int qt = QLO; qt < QHI; ++qt) {
;         sA[qt] = __builtin_amdgcn_mfma_f32_16x16x32_bf16(Kn[0], Qf[qt][0], (f32x4){0.f, 0.f, 0.f, 0.f}, 0, 0, 0); sA[qt] = __builtin_amdgcn_mfma_f32_16x16x32_bf16(Kn[1], Qf[qt][1], sA[qt], 0, 0, 0);
;         sB[qt] = __builtin_amdgcn_mfma_f32_16x16x32_bf16(Kn[2], Qf[qt][0], (f32x4){0.f, 0.f, 0.f, 0.f}, 0, 0, 0); sB[qt] = __builtin_amdgcn_mfma_f32_16x16x32_bf16(Kn[3], Qf[qt][1], sB[qt], 0, 0, 0);
;     }
;     if (DRY != 2) if (on < 27) attn_load_k(pn, C.r4, C.j0, C.rowbase, C.h, C.klo, C.Kr, Kn);
.LBB0_594:
	s_add_i32 s0, s4, 0xfffc
	s_and_b32 s1, s0, 0xff
	s_mulk_i32 s1, 0xab
	s_bfe_u32 s1, s1, 0x70009
	s_mul_i32 s14, s1, 3
	s_sub_i32 s0, s0, s14
	s_mul_i32 s0, s0, 3
	s_add_i32 s0, s1, s0
	s_add_i32 s0, s0, 18
	s_and_b32 s0, s0, 0xff
	s_sub_i32 s0, s0, 18
	s_mul_i32 s14, s0, 0xab
	s_bfe_u32 s14, s14, 0x70009
	s_add_i32 s15, s82, s14
	s_mul_i32 s14, s14, -3
	s_lshl_b32 s1, s83, 12
	s_add_i32 s14, s14, s0
	v_add_u32_e32 v114, s1, v187
	s_xor_b32 s1, s1, 0x1000
	s_and_b32 s15, s15, 3
	s_lshl_b32 s0, s14, 5
	s_add_i32 s1, s59, s1
	s_or_b32 s15, s15, s78
	s_add_i32 s14, s0, s81
	s_add_i32 s0, s0, s79
	s_cmpk_lt_u32 s14, 0x800
	s_cselect_b32 s42, s14, s0
	s_cmpk_lt_u32 s0, 0x800
	s_cselect_b32 s0, s0, s14
	s_lshl_b32 s14, s42, 2
	s_waitcnt vmcnt(3)
	v_mfma_f32_16x16x32_bf16 v[128:131], v[100:103], v[64:67], 0
	s_add_i32 s14, s14, s15
	s_mulk_i32 s14, 0x600
	s_lshl_b32 s0, s0, 2
	s_waitcnt vmcnt(0)
	s_add_i32 s14, s14, s62
	s_add_i32 s0, s0, s15
	s_waitcnt vmcnt(0)
	ds_read_b64_tr_b16 v[124:125], v114
	ds_read_b64_tr_b16 v[120:121], v114 offset:32
	ds_read_b64_tr_b16 v[116:117], v114 offset:1024
	ds_read_b64_tr_b16 v[112:113], v114 offset:1056
	ds_read_b64_tr_b16 v[126:127], v114 offset:2048
	ds_read_b64_tr_b16 v[122:123], v114 offset:2080
	ds_read_b64_tr_b16 v[118:119], v114 offset:3072
	ds_read_b64_tr_b16 v[114:115], v114 offset:3104
	s_lshl_b32 s14, s14, 1
	s_mulk_i32 s0, 0x600
	s_mov_b32 m0, s1
	v_mfma_f32_16x16x32_bf16 v[136:139], v[108:111], v[68:71], v[128:131]
	s_add_i32 s0, s0, s62
	buffer_load_dwordx4 v182, s[8:11], s14 offen lds
	s_add_i32 m0, s1, 0x400
	v_mfma_f32_16x16x32_bf16 v[128:131], v[96:99], v[64:67], 0
	s_lshl_b32 s0, s0, 1
	buffer_load_dwordx4 v186, s[8:11], s14 offen lds
	s_add_i32 m0, s1, 0x800
	v_mfma_f32_16x16x32_bf16 v[100:103], v[100:103], v[72:75], 0
	buffer_load_dwordx4 v182, s[8:11], s0 offen lds
	s_add_i32 m0, s1, 0xc00
	s_mov_b32 s42, s10
	v_mfma_f32_16x16x32_bf16 v[96:99], v[96:99], v[72:75], 0
	buffer_load_dwordx4 v186, s[8:11], s0 offen lds
	s_mov_b32 s43, s11
	v_max_f32_e32 v144, v137, v137
	v_mfma_f32_16x16x32_bf16 v[140:143], v[104:107], v[68:71], v[128:131]
	v_max_f32_e32 v145, v136, v136
	v_max_f32_e32 v144, v145, v144
	v_max_f32_e32 v145, v139, v139
	v_mfma_f32_16x16x32_bf16 v[128:131], v[108:111], v[76:79], v[100:103]
	v_max_f32_e32 v146, v138, v138
	v_max_f32_e32 v145, v146, v145
	s_nop 1
	v_max_f32_e32 v146, v143, v143
	v_mfma_f32_16x16x32_bf16 v[132:135], v[104:107], v[76:79], v[96:99]
	buffer_load_dwordx4 v[100:103], v184, s[40:43], s14 offen
	s_nop 1
	buffer_load_dwordx4 v[96:99], v184, s[40:43], s0 offen
	buffer_load_dwordx4 v[108:111], v185, s[40:43], s14 offen
	buffer_load_dwordx4 v[104:107], v185, s[40:43], s0 offen
	v_max_f32_e32 v147, v142, v142
	v_max_f32_e32 v146, v147, v146
	v_max3_f32 v146, v140, v141, v146
	v_max3_f32 v145, v144, v145, v146
	v_max3_f32 v144, v128, v129, v130
	v_max3_f32 v146, v131, v132, v133
	v_max3_f32 v144, v144, v134, v135
	v_max_f32_e32 v144, v144, v146
	v_add_f32_e32 v146, 0x41000000, v194
	v_cmp_gt_f32_e32 vcc, v145, v146
	v_add_f32_e32 v146, 0x41000000, v193
	v_cmp_gt_f32_e64 s[0:1], v144, v146
	s_or_b64 vcc, vcc, s[0:1]
	s_cbranch_vccz .LBB0_593
	v_mov_b32_e32 v146, v145
	s_nop 1
	v_permlane16_swap_b32_e32 v145, v146
	v_max_f32_e32 v145, v145, v146
	v_mov_b32_e32 v146, v145
	s_nop 1
	v_permlane32_swap_b32_e32 v145, v146
	v_max_f32_e32 v145, v145, v146
	v_mov_b32_e32 v146, v144
	s_nop 1
	v_permlane16_swap_b32_e32 v144, v146
	v_max_f32_e32 v144, v144, v146
	v_mov_b32_e32 v146, v144
	s_nop 1
	v_permlane32_swap_b32_e32 v144, v146
	v_max_f32_e32 v144, v144, v146
	v_max_f32_e32 v145, v145, v145
	v_max_f32_e32 v146, v194, v194
	v_max_f32_e32 v145, v146, v145
	v_sub_f32_e32 v146, v194, v145
	v_exp_f32_e32 v146, v146
	v_max_f32_e32 v144, v144, v144
	v_mov_b32_e32 v194, v145
	v_pk_mul_f32 v[62:63], v[62:63], v[146:147] op_sel_hi:[1,0]
	v_pk_mul_f32 v[60:61], v[60:61], v[146:147] op_sel_hi:[1,0]
	v_pk_mul_f32 v[58:59], v[58:59], v[146:147] op_sel_hi:[1,0]
	v_pk_mul_f32 v[56:57], v[56:57], v[146:147] op_sel_hi:[1,0]
	v_pk_mul_f32 v[54:55], v[54:55], v[146:147] op_sel_hi:[1,0]
	v_pk_mul_f32 v[52:53], v[52:53], v[146:147] op_sel_hi:[1,0]
	v_pk_mul_f32 v[50:51], v[50:51], v[146:147] op_sel_hi:[1,0]
	v_pk_mul_f32 v[48:49], v[48:49], v[146:147] op_sel_hi:[1,0]
	v_max_f32_e32 v147, v193, v193
	v_max_f32_e32 v148, v147, v144
	v_sub_f32_e32 v144, v193, v148
	v_exp_f32_e32 v147, v144
	v_mov_b32_e32 v193, v148
	v_mov_b32_e32 v144, v147
	v_mul_f32_e32 v178, v178, v146
	v_mul_f32_e32 v179, v179, v147
	v_pk_mul_f32 v[46:47], v[46:47], v[144:145] op_sel_hi:[1,0]
	v_pk_mul_f32 v[44:45], v[44:45], v[144:145] op_sel_hi:[1,0]
	v_pk_mul_f32 v[42:43], v[42:43], v[144:145] op_sel_hi:[1,0]
	v_pk_mul_f32 v[40:41], v[40:41], v[144:145] op_sel_hi:[1,0]
	v_pk_mul_f32 v[38:39], v[38:39], v[144:145] op_sel_hi:[1,0]
	v_pk_mul_f32 v[36:37], v[36:37], v[144:145] op_sel_hi:[1,0]
	v_pk_mul_f32 v[34:35], v[34:35], v[144:145] op_sel_hi:[1,0]
	v_pk_mul_f32 v[32:33], v[32:33], v[144:145] op_sel_hi:[1,0]
	s_branch .LBB0_593

; __device__ __forceinline__ u32x4 pack8(f32x4 a, f32x4 b) { u32x4 w; w.x = cvt_pk_bf16(a[0], a[1]); w.y = cvt_pk_bf16(a[2], a[3]); w.z = cvt_pk_bf16(b[0], b[1]); w.w = cvt_pk_bf16(b[2], b[3]); return w; }
; template <int MODE  , int QLO, int QHI> ...
;     ...
; #pragma unroll
;         for (int qt = QLO; qt < QHI; ++qt) {
;             const int TA = jtA - (j0 + 16 * qt), TB = TA + 16;
;             const bool rA = vA && (same ? (TA >= -256 && TA <= 256) : (TA >= -16 && TA <= 16));
;             const bool rB = vB && (same ? (TB >= -256 && TB <= 256) : (TB >= -16 && TB <= 16));
;             const int ixA = same ? ((TA + 256) >> 4) : (33 + (dr + 3) * 3 + ((TA + 16) >> 4));
;             const f32x4 cAq = ctf[(rA ? ixA : 54) * 64 + lane], cBq = ctf[(rB ? ixA + 1 : 54) * 64 + lane];
;             const f32x4 dA = sA[qt] - mrun[qt], dB = sB[qt] - mrun[qt];
;             f32x4 eA, eB;
; #pragma unroll
;             for (int r = 0; r < 4; ++r) { eA[r] = __builtin_amdgcn_exp2f(dA[r]); eB[r] = __builtin_amdgcn_exp2f(dB[r]); }
;             const f32x4 pA = cAq * eA, pB = cBq * eB;
;             const f32x4 sm = pA + pB;
;             lrun[qt] += (sm[0] + sm[1]) + (sm[2] + sm[3]);
;             const bf16x8 P = __builtin_bit_cast(bf16x8, pg8::pack8(pA, pB));
; #pragma unroll
;             for (int dt = 0; dt < 4; ++dt) O[qt][dt] = __builtin_amdgcn_mfma_f32_16x16x32_bf16(Vf[dt], P, O[qt][dt], 0, 0, 0);
;         }
.LBB0_598:
	s_and_b32 s0, s48, 0xff
	s_sub_i32 s0, s0, 18
	s_mul_i32 s1, s0, 0xab
	s_bfe_u32 s1, s1, 0x70009
	s_add_i32 s4, s82, s1
	s_mul_i32 s1, s1, -3
	s_add_i32 s1, s1, s0
	s_and_b32 s4, s4, 3
	s_lshl_b32 s0, s1, 5
	s_add_i32 s14, s0, s81
	s_xor_b32 s83, s83, 1
	s_sub_i32 s15, s4, s75
	s_add_i32 s0, s0, s79
	s_cmpk_lt_u32 s0, 0x800
	s_cselect_b64 s[0:1], -1, 0
	s_cmpk_lt_u32 s14, 0x800
	s_cselect_b64 s[4:5], -1, 0
	s_mul_i32 s42, s15, 3
	s_sub_i32 s43, s14, s79
	s_add_i32 s42, s42, 42
	s_add_i32 s49, s43, 16
	s_cmp_lt_u32 s49, 33
	s_cselect_b64 s[14:15], -1, 0
	s_and_b64 s[64:65], s[4:5], s[14:15]
	s_add_i32 s58, s43, 32
	s_cmp_lt_u32 s58, 33
	s_cselect_b64 s[66:67], -1, 0
	s_lshr_b32 s49, s49, 4
	s_add_i32 s49, s49, s42
	s_and_b64 s[66:67], s[0:1], s[66:67]
	s_lshl_b32 s49, s49, 6
	s_and_b64 s[64:65], s[64:65], exec
	s_cselect_b32 s58, s49, 0xd80
	s_add_i32 s49, s49, 64
	s_and_b64 s[64:65], s[66:67], exec
	s_cselect_b32 s49, s49, 0xd80
	s_cmp_lt_u32 s43, 33
	v_lshl_add_u32 v195, s49, 4, v188
	s_cselect_b64 s[64:65], -1, 0
	s_lshr_b32 s49, s43, 4
	v_lshl_add_u32 v161, s58, 4, v188
	v_sub_f32_e32 v152, v152, v194
	v_sub_f32_e32 v153, v153, v194
	s_add_i32 s49, s49, s42
	ds_read_b128 v[196:199], v161
	ds_read_b128 v[200:203], v195
	v_exp_f32_e32 v204, v152
	v_sub_f32_e32 v152, v156, v194
	v_exp_f32_e32 v205, v153
	v_sub_f32_e32 v153, v157, v194
	v_sub_f32_e32 v154, v154, v194
	v_sub_f32_e32 v155, v155, v194
	s_and_b64 s[66:67], s[4:5], s[64:65]
	s_and_b64 s[14:15], s[0:1], s[14:15]
	s_lshl_b32 s49, s49, 6
	v_exp_f32_e32 v152, v152
	v_exp_f32_e32 v208, v154
	v_sub_f32_e32 v154, v158, v194
	v_exp_f32_e32 v209, v155
	v_sub_f32_e32 v155, v159, v194
	v_exp_f32_e32 v153, v153
	s_and_b64 s[66:67], s[66:67], exec
	v_exp_f32_e32 v154, v154
	v_exp_f32_e32 v155, v155
	s_cselect_b32 s58, s49, 0xd80
	s_add_i32 s49, s49, 64
	s_and_b64 s[14:15], s[14:15], exec
	s_cselect_b32 s14, s49, 0xd80
	s_add_i32 s49, s43, -16
	s_waitcnt lgkmcnt(1)
	v_mul_f32_e32 v156, v198, v208
	v_mul_f32_e32 v157, v199, v209
	v_mul_f32_e32 v158, v196, v204
	v_mul_f32_e32 v159, v197, v205
	s_waitcnt lgkmcnt(0)
	v_mul_f32_e32 v200, v200, v152
	v_mul_f32_e32 v201, v201, v153
	v_cvt_pk_bf16_f32 v152, v158, v159
	s_cmp_lt_u32 s49, 33
	v_mul_f32_e32 v202, v202, v154
	v_mul_f32_e32 v203, v203, v155
	v_cvt_pk_bf16_f32 v153, v156, v157
	v_cvt_pk_bf16_f32 v154, v200, v201
	v_lshl_add_u32 v156, s14, 4, v188
	v_cvt_pk_bf16_f32 v155, v202, v203
	v_sub_f32_e32 v144, v144, v193
	v_mfma_f32_16x16x32_bf16 v[60:63], v[124:127], v[152:155], v[60:63]
	v_sub_f32_e32 v145, v145, v193
	v_sub_f32_e32 v146, v146, v193
	v_sub_f32_e32 v147, v147, v193
	v_mfma_f32_16x16x32_bf16 v[56:59], v[120:123], v[152:155], v[56:59]
	s_cselect_b64 s[14:15], -1, 0
	s_lshr_b32 s49, s49, 4
	v_exp_f32_e32 v210, v144
	v_mfma_f32_16x16x32_bf16 v[52:55], v[116:119], v[152:155], v[52:55]
	v_sub_f32_e32 v144, v148, v193
	v_exp_f32_e32 v211, v145
	v_sub_f32_e32 v145, v149, v193
	v_mfma_f32_16x16x32_bf16 v[48:51], v[112:115], v[152:155], v[48:51]
	v_lshl_add_u32 v152, s58, 4, v188
	ds_read_b128 v[152:155], v152
	ds_read_b128 v[156:159], v156
	v_exp_f32_e32 v148, v146
	v_sub_f32_e32 v146, v150, v193
	v_exp_f32_e32 v149, v147
	v_sub_f32_e32 v147, v151, v193
	s_add_i32 s49, s49, s42
	v_exp_f32_e32 v144, v144
	v_exp_f32_e32 v146, v146
	v_exp_f32_e32 v147, v147
	v_exp_f32_e32 v145, v145
	s_and_b64 s[66:67], s[4:5], s[14:15]
	s_and_b64 s[64:65], s[0:1], s[64:65]
	s_lshl_b32 s49, s49, 6
	s_and_b64 s[66:67], s[66:67], exec
	s_cselect_b32 s58, s49, 0xd80
	s_add_i32 s49, s49, 64
	s_and_b64 s[64:65], s[64:65], exec
	s_waitcnt lgkmcnt(1)
	v_mul_f32_e32 v150, v148, v154
	v_mul_f32_e32 v151, v149, v155
	v_mul_f32_e32 v212, v210, v152
	v_mul_f32_e32 v213, v211, v153
	s_waitcnt lgkmcnt(0)
	v_mul_f32_e32 v158, v146, v158
	v_mul_f32_e32 v159, v147, v159
	v_mul_f32_e32 v156, v144, v156
	v_mul_f32_e32 v157, v145, v157
	v_cvt_pk_bf16_f32 v144, v212, v213
	s_cselect_b32 s49, s49, 0xd80
	s_sub_i32 s43, s43, 32
	v_cvt_pk_bf16_f32 v145, v150, v151
	v_cvt_pk_bf16_f32 v146, v156, v157
	v_cvt_pk_bf16_f32 v147, v158, v159
	v_fma_f32 v150, v196, v204, v200
	v_fma_f32 v151, v197, v205, v201
	v_mfma_f32_16x16x32_bf16 v[44:47], v[124:127], v[144:147], v[44:47]
	v_fma_f32 v154, v148, v154, v158
	v_fma_f32 v155, v149, v155, v159
	v_fma_f32 v152, v210, v152, v156
	v_fma_f32 v153, v211, v153, v157
	v_lshl_add_u32 v148, s49, 4, v188
	v_mfma_f32_16x16x32_bf16 v[40:43], v[120:123], v[144:147], v[40:43]
	v_sub_f32_e32 v136, v136, v192
	v_sub_f32_e32 v137, v137, v192
	v_sub_f32_e32 v138, v138, v192
	v_mfma_f32_16x16x32_bf16 v[36:39], v[116:119], v[144:147], v[36:39]
	v_sub_f32_e32 v139, v139, v192
	s_cmp_lt_u32 s43, 33
	v_mov_b32_e32 v156, v150
	v_mfma_f32_16x16x32_bf16 v[32:35], v[112:115], v[144:147], v[32:35]
	v_lshl_add_u32 v144, s58, 4, v188
	v_mov_b32_e32 v157, v152
	v_mov_b32_e32 v152, v151
	ds_read_b128 v[144:147], v144
	ds_read_b128 v[148:151], v148
	v_exp_f32_e32 v158, v136
	v_sub_f32_e32 v136, v140, v192
	v_exp_f32_e32 v159, v137
	v_sub_f32_e32 v137, v141, v192
	v_exp_f32_e32 v140, v138
	v_exp_f32_e32 v141, v139
	s_cselect_b64 s[64:65], -1, 0
	s_and_b64 s[0:1], s[0:1], s[14:15]
	s_lshr_b32 s14, s43, 4
	v_exp_f32_e32 v136, v136
	v_sub_f32_e32 v138, v142, v192
	v_sub_f32_e32 v139, v143, v192
	v_exp_f32_e32 v137, v137
	s_add_i32 s14, s14, s42
	v_exp_f32_e32 v138, v138
	v_exp_f32_e32 v139, v139
	s_and_b64 s[4:5], s[4:5], s[64:65]
	s_lshl_b32 s14, s14, 6
	s_and_b64 s[4:5], s[4:5], exec
	v_fma_f32 v198, v198, v208, v202
	v_fma_f32 v199, v199, v209, v203
	s_waitcnt lgkmcnt(1)
; template <int MODE  , int QLO, int QHI> ...
;     ...
; #pragma unroll
;         for (int qt = QLO; qt < QHI; ++qt) {
;             const int TA = jtA - (j0 + 16 * qt), TB = TA + 16;
;             const bool rA = vA && (same ? (TA >= -256 && TA <= 256) : (TA >= -16 && TA <= 16));
;             const bool rB = vB && (same ? (TB >= -256 && TB <= 256) : (TB >= -16 && TB <= 16));
;             const int ixA = same ? ((TA + 256) >> 4) : (33 + (dr + 3) * 3 + ((TA + 16) >> 4));
;             const f32x4 cAq = ctf[(rA ? ixA : 54) * 64 + lane], cBq = ctf[(rB ? ixA + 1 : 54) * 64 + lane];
;             const f32x4 dA = sA[qt] - mrun[qt], dB = sB[qt] - mrun[qt];
;             f32x4 eA, eB;
; #pragma unroll
;             for (int r = 0; r < 4; ++r) { eA[r] = __builtin_amdgcn_exp2f(dA[r]); eB[r] = __builtin_amdgcn_exp2f(dB[r]); }
;             const f32x4 pA = cAq * eA, pB = cBq * eB;
;             const f32x4 sm = pA + pB;
;             lrun[qt] += (sm[0] + sm[1]) + (sm[2] + sm[3]);
;             const bf16x8 P = __builtin_bit_cast(bf16x8, pg8::pack8(pA, pB));
; #pragma unroll
;             for (int dt = 0; dt < 4; ++dt) O[qt][dt] = __builtin_amdgcn_mfma_f32_16x16x32_bf16(Vf[dt], P, O[qt][dt], 0, 0, 0);
;         }
; template <int MODE, int DRY, int QLO, int QHI>
; __device__ __forceinline__ int attn_step(int o, int& par, const AttnCtx& C, const AttnLane& L, f32x4 (&O)[4][4], float (&mrun)[4], float (&lrun)[4], const bf16x8 (&Qf)[4][2], bf16x8 (&Kn)[4]) {
;     ...
;     asm volatile("s_waitcnt vmcnt(0)" ::: "memory");
;     bf16x8 Vf[4];
;     { LAS const unsigned char* vb = C.vl + par * 4096 + (4 * fq + (fr >> 2)) * 64 + (fr & 3) * 8;
; #pragma unroll
;       for (int dt = 0; dt < 4; ++dt) { const s16x4 lo = vtr(vb + (dt >> 1) * 1024 + (dt & 1) * 32), hi = vtr(vb + 2048 + (dt >> 1) * 1024 + (dt & 1) * 32);
;           Vf[dt] = (bf16x8){lo[0], lo[1], lo[2], lo[3], hi[0], hi[1], hi[2], hi[3]}; }
;       asm volatile("" ::: "memory"); }
;     if (DRY != 2) if (on < 27) attn_dma_v(pn, C.r4, C.j0, C.rowbase, C.h, C.vlo, C.Vr, C.vl + (par ^ 1) * 4096);
;     par ^= 1;
;     if (DRY == 1) {
;         asm volatile("" :: "v"(Kn[0]), "v"(Kn[1]), "v"(Kn[2]), "v"(Kn[3]), "v"(Vf[0]), "v"(Vf[1]), "v"(Vf[2]), "v"(Vf[3]));
;         if (on < 27) attn_load_k(pn, C.r4, C.j0, C.rowbase, C.h, C.klo, C.Kr, Kn);
;         return on;
;     }
;     f32x4 sA[4], sB[4];
; #pragma unroll
	v_mul_f32_e32 v142, v140, v146
	v_mul_f32_e32 v143, v141, v147
	s_cselect_b32 s4, s14, 0xd80
	s_add_i32 s14, s14, 64
	v_mul_f32_e32 v196, v158, v144
	v_mul_f32_e32 v197, v159, v145
	s_waitcnt lgkmcnt(0)
	v_mul_f32_e32 v148, v136, v148
	v_mul_f32_e32 v149, v137, v149
	v_cvt_pk_bf16_f32 v136, v196, v197
	v_cvt_pk_bf16_f32 v137, v142, v143
	v_add_f32_e32 v142, v156, v152
	v_add_f32_e32 v143, v157, v153
	v_mov_b32_e32 v152, v198
	v_mov_b32_e32 v153, v154
	v_mov_b32_e32 v154, v199
	s_and_b64 s[0:1], s[0:1], exec
	v_mul_f32_e32 v150, v138, v150
	v_mul_f32_e32 v151, v139, v151
	v_add_f32_e32 v152, v152, v154
	v_add_f32_e32 v153, v153, v155
	s_cselect_b32 s0, s14, 0xd80
	v_cvt_pk_bf16_f32 v138, v148, v149
	v_cvt_pk_bf16_f32 v139, v150, v151
	v_add_f32_e32 v142, v142, v152
	v_add_f32_e32 v143, v143, v153
	v_mfma_f32_16x16x32_bf16 v[28:31], v[124:127], v[136:139], v[28:31]
	v_fma_f32 v146, v140, v146, v150
	v_fma_f32 v147, v141, v147, v151
	v_lshl_add_u32 v140, s0, 4, v188
	v_add_f32_e32 v178, v178, v142
	v_add_f32_e32 v179, v179, v143
	v_mfma_f32_16x16x32_bf16 v[24:27], v[120:123], v[136:139], v[24:27]
	v_sub_f32_e32 v132, v132, v167
	v_sub_f32_e32 v133, v133, v167
	v_sub_f32_e32 v128, v128, v167
	v_mfma_f32_16x16x32_bf16 v[20:23], v[116:119], v[136:139], v[20:23]
	v_exp_f32_e32 v132, v132
	v_sub_f32_e32 v129, v129, v167
	v_sub_f32_e32 v134, v134, v167
	v_mfma_f32_16x16x32_bf16 v[16:19], v[112:115], v[136:139], v[16:19]
	v_lshl_add_u32 v136, s4, 4, v188
	ds_read_b128 v[136:139], v136
	ds_read_b128 v[140:143], v140
	v_sub_f32_e32 v135, v135, v167
	v_exp_f32_e32 v133, v133
	v_exp_f32_e32 v128, v128
	v_exp_f32_e32 v129, v129
	v_sub_f32_e32 v130, v130, v167
	v_exp_f32_e32 v134, v134
	v_sub_f32_e32 v131, v131, v167
	v_exp_f32_e32 v135, v135
	v_exp_f32_e32 v130, v130
	v_exp_f32_e32 v131, v131
	s_waitcnt lgkmcnt(0)
	v_mul_f32_e32 v132, v132, v140
	v_mul_f32_e32 v133, v133, v141
	v_fma_f32 v144, v158, v144, v148
	v_fma_f32 v145, v159, v145, v149
	v_mul_f32_e32 v150, v128, v136
	v_mul_f32_e32 v151, v129, v137
	v_mul_f32_e32 v134, v134, v142
	v_mul_f32_e32 v135, v135, v143
	v_fma_f32 v128, v128, v136, v132
	v_fma_f32 v129, v129, v137, v133
	v_mul_f32_e32 v148, v130, v138
	v_mul_f32_e32 v149, v131, v139
	v_fma_f32 v138, v130, v138, v134
	v_fma_f32 v139, v131, v139, v135
	v_mov_b32_e32 v130, v144
	v_mov_b32_e32 v131, v128
	v_mov_b32_e32 v128, v145
	v_add_f32_e32 v136, v130, v128
	v_add_f32_e32 v137, v131, v129
	v_cvt_pk_bf16_f32 v128, v150, v151
	v_cvt_pk_bf16_f32 v129, v148, v149
	v_cvt_pk_bf16_f32 v130, v132, v133
	v_cvt_pk_bf16_f32 v131, v134, v135
	s_add_i32 s33, s33, 1
	v_mfma_f32_16x16x32_bf16 v[12:15], v[124:127], v[128:131], v[12:15]
	v_mov_b32_e32 v124, v146
	v_mov_b32_e32 v125, v138
	v_mov_b32_e32 v138, v147
	v_mfma_f32_16x16x32_bf16 v[8:11], v[120:123], v[128:131], v[8:11]
	v_add_f32_e64 v120, v124, v138
	v_add_f32_e64 v121, v125, v139
	s_add_i32 s48, s48, 3
	v_add_f32_e32 v120, v136, v120
	v_add_f32_e32 v121, v137, v121
	v_mfma_f32_16x16x32_bf16 v[4:7], v[116:119], v[128:131], v[4:7]
	v_add_f32_e64 v170, v170, v120
	v_add_f32_e64 v171, v171, v121
	s_cmp_gt_u32 s33, 10
	v_mfma_f32_16x16x32_bf16 v[0:3], v[112:115], v[128:131], v[0:3]
	s_cbranch_scc1 .LBB0_603
.LBB0_599:
	s_add_i32 s0, s33, 0xfffc
	s_and_b32 s1, s0, 0xff
	s_mulk_i32 s1, 0xab
	s_bfe_u32 s1, s1, 0x70009
	s_mul_i32 s4, s1, 3
	s_sub_i32 s0, s0, s4
	s_mul_i32 s0, s0, 3
	s_add_i32 s0, s1, s0
	s_add_i32 s0, s0, 18
	s_waitcnt vmcnt(2)
	v_mfma_f32_16x16x32_bf16 v[128:131], v[96:99], v[64:67], 0
	s_and_b32 s0, s0, 0xff
	s_sub_i32 s0, s0, 18
	s_mul_i32 s4, s0, 0xab
	s_waitcnt vmcnt(0)
	v_mfma_f32_16x16x32_bf16 v[156:159], v[104:107], v[68:71], v[128:131]
	s_bfe_u32 s4, s4, 0x70009
	s_add_i32 s5, s82, s4
	s_mul_i32 s4, s4, -3
	v_mfma_f32_16x16x32_bf16 v[128:131], v[100:103], v[72:75], 0
	s_lshl_b32 s1, s83, 12
	s_add_i32 s4, s4, s0
	v_add_u32_e32 v132, s1, v187
	s_xor_b32 s1, s1, 0x1000
	s_and_b32 s5, s5, 3
	s_lshl_b32 s0, s4, 5
	s_add_i32 s1, s59, s1
	v_mfma_f32_16x16x32_bf16 v[144:147], v[108:111], v[76:79], v[128:131]
	s_or_b32 s5, s5, s78
	s_add_i32 s4, s0, s81
	s_add_i32 s0, s0, s79
	v_mfma_f32_16x16x32_bf16 v[128:131], v[96:99], v[72:75], 0
	s_cmpk_lt_u32 s4, 0x800
	s_cselect_b32 s14, s4, s0
	s_cmpk_lt_u32 s0, 0x800
	v_mfma_f32_16x16x32_bf16 v[112:115], v[100:103], v[64:67], 0
	s_cselect_b32 s0, s0, s4
	s_lshl_b32 s4, s14, 2
	s_add_i32 s4, s4, s5
	v_mfma_f32_16x16x32_bf16 v[148:151], v[104:107], v[76:79], v[128:131]
	s_mulk_i32 s4, 0x600
	s_lshl_b32 s0, s0, 2
	s_waitcnt vmcnt(0)
; #define LAS __attribute__((address_space(3)))
; template <int MODE  , int QLO, int QHI> ...
;     ...
;         float tmax[4];
; #pragma unroll
;         for (int qt = QLO; qt < QHI; ++qt) {
;             const float a = fmaxf(fmaxf(fmaxf(sA[qt][0], sA[qt][1]), fmaxf(sA[qt][2], sA[qt][3])), fmaxf(fmaxf(sB[qt][0], sB[qt][1]), fmaxf(sB[qt][2], sB[qt][3])));
;             tmax[qt] = xmax16_32(a);
;         }
;         bool need = false;
; #pragma unroll
;         for (int qt = QLO; qt < QHI; ++qt) need = need || (tmax[qt] > mrun[qt] + 8.f);
;         if (__builtin_amdgcn_ballot_w64(need) != 0ull) {
; #pragma unroll
;             for (int qt = QLO; qt < QHI; ++qt) {
; template <int MODE, int DRY, int QLO, int QHI>
; __device__ __forceinline__ int attn_step(int o, int& par, const AttnCtx& C, const AttnLane& L, f32x4 (&O)[4][4], float (&mrun)[4], float (&lrun)[4], const bf16x8 (&Qf)[4][2], bf16x8 (&Kn)[4]) {
;     ...
;     asm volatile("s_waitcnt vmcnt(0)" ::: "memory");
;     bf16x8 Vf[4];
;     { LAS const unsigned char* vb = C.vl + par * 4096 + (4 * fq + (fr >> 2)) * 64 + (fr & 3) * 8;
; #pragma unroll
;       for (int dt = 0; dt < 4; ++dt) { const s16x4 lo = vtr(vb + (dt >> 1) * 1024 + (dt & 1) * 32), hi = vtr(vb + 2048 + (dt >> 1) * 1024 + (dt & 1) * 32);
;           Vf[dt] = (bf16x8){lo[0], lo[1], lo[2], lo[3], hi[0], hi[1], hi[2], hi[3]}; }
;       asm volatile("" ::: "memory"); }
;     if (DRY != 2) if (on < 27) attn_dma_v(pn, C.r4, C.j0, C.rowbase, C.h, C.vlo, C.Vr, C.vl + (par ^ 1) * 4096);
;     par ^= 1;
;     if (DRY == 1) {
;         asm volatile("" :: "v"(Kn[0]), "v"(Kn[1]), "v"(Kn[2]), "v"(Kn[3]), "v"(Vf[0]), "v"(Vf[1]), "v"(Vf[2]), "v"(Vf[3]));
;         if (on < 27) attn_load_k(pn, C.r4, C.j0, C.rowbase, C.h, C.klo, C.Kr, Kn);
;         return on;
;     }
;     f32x4 sA[4], sB[4];
; #pragma unroll
;     for (int qt = QLO; qt < QHI; ++qt) {
;         sA[qt] = __builtin_amdgcn_mfma_f32_16x16x32_bf16(Kn[0], Qf[qt][0], (f32x4){0.f, 0.f, 0.f, 0.f}, 0, 0, 0); sA[qt] = __builtin_amdgcn_mfma_f32_16x16x32_bf16(Kn[1], Qf[qt][1], sA[qt], 0, 0, 0);
;         sB[qt] = __builtin_amdgcn_mfma_f32_16x16x32_bf16(Kn[2], Qf[qt][0], (f32x4){0.f, 0.f, 0.f, 0.f}, 0, 0, 0); sB[qt] = __builtin_amdgcn_mfma_f32_16x16x32_bf16(Kn[3], Qf[qt][1], sB[qt], 0, 0, 0);
;     }
;     if (DRY != 2) if (on < 27) attn_load_k(pn, C.r4, C.j0, C.rowbase, C.h, C.klo, C.Kr, Kn);
	v_mfma_f32_16x16x32_bf16 v[128:131], v[100:103], v[80:83], 0
	s_add_i32 s4, s4, s62
	s_add_i32 s0, s0, s5
	s_lshl_b32 s4, s4, 1
	v_mfma_f32_16x16x32_bf16 v[152:155], v[108:111], v[68:71], v[112:115]
	ds_read_b64_tr_b16 v[124:125], v132
	ds_read_b64_tr_b16 v[120:121], v132 offset:32
	ds_read_b64_tr_b16 v[116:117], v132 offset:1024
	ds_read_b64_tr_b16 v[112:113], v132 offset:1056
	ds_read_b64_tr_b16 v[126:127], v132 offset:2048
	ds_read_b64_tr_b16 v[122:123], v132 offset:2080
	ds_read_b64_tr_b16 v[118:119], v132 offset:3072
	ds_read_b64_tr_b16 v[114:115], v132 offset:3104
	s_mulk_i32 s0, 0x600
	s_mov_b32 m0, s1
	v_mfma_f32_16x16x32_bf16 v[136:139], v[108:111], v[84:87], v[128:131]
	s_add_i32 s0, s0, s62
	buffer_load_dwordx4 v182, s[8:11], s4 offen lds
	s_add_i32 m0, s1, 0x400
	v_mfma_f32_16x16x32_bf16 v[128:131], v[96:99], v[80:83], 0
	s_lshl_b32 s0, s0, 1
	buffer_load_dwordx4 v186, s[8:11], s4 offen lds
	s_add_i32 m0, s1, 0x800
	v_mfma_f32_16x16x32_bf16 v[100:103], v[100:103], v[88:91], 0
	buffer_load_dwordx4 v182, s[8:11], s0 offen lds
	s_add_i32 m0, s1, 0xc00
	s_mov_b32 s42, s10
	v_mfma_f32_16x16x32_bf16 v[96:99], v[96:99], v[88:91], 0
	buffer_load_dwordx4 v186, s[8:11], s0 offen lds
	s_mov_b32 s43, s11
	v_max_f32_e32 v161, v153, v153
	v_mfma_f32_16x16x32_bf16 v[140:143], v[104:107], v[84:87], v[128:131]
	v_max_f32_e32 v195, v152, v152
	v_max_f32_e32 v161, v195, v161
	v_max_f32_e32 v195, v155, v155
	v_mfma_f32_16x16x32_bf16 v[128:131], v[108:111], v[92:95], v[100:103]
	v_max_f32_e32 v196, v154, v154
	v_max_f32_e32 v195, v196, v195
	v_max_f32_e32 v196, v159, v159
	v_mfma_f32_16x16x32_bf16 v[132:135], v[104:107], v[92:95], v[96:99]
	buffer_load_dwordx4 v[100:103], v184, s[40:43], s4 offen
	s_nop 1
	buffer_load_dwordx4 v[96:99], v184, s[40:43], s0 offen
	buffer_load_dwordx4 v[108:111], v185, s[40:43], s4 offen
	buffer_load_dwordx4 v[104:107], v185, s[40:43], s0 offen
	v_max_f32_e32 v197, v158, v158
	v_max_f32_e32 v196, v197, v196
	v_max3_f32 v196, v156, v157, v196
	v_max3_f32 v197, v161, v195, v196
	v_max3_f32 v161, v144, v145, v146
	v_max3_f32 v195, v147, v148, v149
	v_max3_f32 v161, v161, v150, v151
	v_max_f32_e32 v196, v161, v195
	v_max3_f32 v161, v136, v137, v138
	v_max3_f32 v195, v139, v140, v141
	v_max3_f32 v161, v161, v142, v143
	v_max_f32_e32 v195, v161, v195
	v_max3_f32 v161, v128, v129, v130
	v_max3_f32 v198, v131, v132, v133
	v_max3_f32 v161, v161, v134, v135
	v_max_f32_e32 v161, v161, v198
	v_add_f32_e32 v198, 0x41000000, v194
	v_cmp_gt_f32_e32 vcc, v197, v198
	v_add_f32_e32 v198, 0x41000000, v193
	v_cmp_gt_f32_e64 s[0:1], v196, v198
	v_add_f32_e32 v198, 0x41000000, v192
	s_or_b64 s[0:1], vcc, s[0:1]
	v_cmp_gt_f32_e32 vcc, v195, v198
	v_add_f32_e32 v198, 0x41000000, v167
	s_or_b64 s[0:1], s[0:1], vcc
	v_cmp_gt_f32_e32 vcc, v161, v198
	s_or_b64 vcc, s[0:1], vcc
	s_cbranch_vccz .LBB0_598
	v_mov_b32_e32 v198, v197
	s_nop 1
	v_permlane16_swap_b32_e32 v197, v198
	v_max_f32_e32 v197, v197, v198
	v_mov_b32_e32 v198, v197
	s_nop 1
	v_permlane32_swap_b32_e32 v197, v198
	v_max_f32_e32 v197, v197, v198
	v_mov_b32_e32 v198, v196
	s_nop 1
	v_permlane16_swap_b32_e32 v196, v198
	v_max_f32_e32 v196, v196, v198
	v_mov_b32_e32 v198, v196
	s_nop 1
	v_permlane32_swap_b32_e32 v196, v198
	v_max_f32_e32 v196, v196, v198
	v_mov_b32_e32 v198, v195
	s_nop 1
	v_permlane16_swap_b32_e32 v195, v198
	v_max_f32_e32 v195, v195, v198
	v_mov_b32_e32 v198, v195
	s_nop 1
	v_permlane32_swap_b32_e32 v195, v198
	v_max_f32_e32 v195, v195, v198
	v_mov_b32_e32 v198, v161
	s_nop 1
	v_permlane16_swap_b32_e32 v161, v198
	v_max_f32_e32 v161, v161, v198
	v_mov_b32_e32 v198, v161
	s_nop 1
	v_permlane32_swap_b32_e32 v161, v198
	v_max_f32_e32 v161, v161, v198
	v_max_f32_e32 v197, v197, v197
	v_max_f32_e32 v198, v194, v194
	v_max_f32_e32 v197, v198, v197
	v_sub_f32_e32 v194, v194, v197
	v_exp_f32_e32 v198, v194
	v_max_f32_e32 v194, v196, v196
	v_max_f32_e32 v196, v193, v193
	v_max_f32_e32 v196, v196, v194
	v_sub_f32_e32 v193, v193, v196
	v_pk_mul_f32 v[62:63], v[62:63], v[198:199] op_sel_hi:[1,0]
	v_pk_mul_f32 v[60:61], v[60:61], v[198:199] op_sel_hi:[1,0]
	v_pk_mul_f32 v[58:59], v[58:59], v[198:199] op_sel_hi:[1,0]
	v_pk_mul_f32 v[56:57], v[56:57], v[198:199] op_sel_hi:[1,0]
	v_pk_mul_f32 v[54:55], v[54:55], v[198:199] op_sel_hi:[1,0]
	v_pk_mul_f32 v[52:53], v[52:53], v[198:199] op_sel_hi:[1,0]
	v_pk_mul_f32 v[50:51], v[50:51], v[198:199] op_sel_hi:[1,0]
	v_pk_mul_f32 v[48:49], v[48:49], v[198:199] op_sel_hi:[1,0]
	v_exp_f32_e32 v199, v193
	v_max_f32_e32 v193, v195, v195
	v_max_f32_e32 v161, v161, v161
	v_mov_b32_e32 v194, v199
	v_pk_mul_f32 v[46:47], v[46:47], v[194:195] op_sel_hi:[1,0]
	v_pk_mul_f32 v[44:45], v[44:45], v[194:195] op_sel_hi:[1,0]
	v_max_f32_e32 v195, v192, v192
	v_max_f32_e32 v195, v195, v193
	v_sub_f32_e32 v192, v192, v195
	v_exp_f32_e32 v192, v192
	v_mul_f32_e32 v178, v178, v198
	v_mul_f32_e32 v179, v179, v199
	v_pk_mul_f32 v[42:43], v[42:43], v[194:195] op_sel_hi:[1,0]
	v_pk_mul_f32 v[40:41], v[40:41], v[194:195] op_sel_hi:[1,0]
	v_pk_mul_f32 v[30:31], v[30:31], v[192:193] op_sel_hi:[1,0]
	v_pk_mul_f32 v[28:29], v[28:29], v[192:193] op_sel_hi:[1,0]
	v_pk_mul_f32 v[26:27], v[26:27], v[192:193] op_sel_hi:[1,0]
	v_pk_mul_f32 v[24:25], v[24:25], v[192:193] op_sel_hi:[1,0]
	v_pk_mul_f32 v[22:23], v[22:23], v[192:193] op_sel_hi:[1,0]
	v_pk_mul_f32 v[20:21], v[20:21], v[192:193] op_sel_hi:[1,0]
	v_pk_mul_f32 v[18:19], v[18:19], v[192:193] op_sel_hi:[1,0]
	v_pk_mul_f32 v[16:17], v[16:17], v[192:193] op_sel_hi:[1,0]
	v_max_f32_e32 v193, v167, v167
	v_max_f32_e32 v161, v193, v161
	v_sub_f32_e32 v167, v167, v161
	v_exp_f32_e32 v193, v167
	v_pk_mul_f32 v[38:39], v[38:39], v[194:195] op_sel_hi:[1,0]
	v_pk_mul_f32 v[36:37], v[36:37], v[194:195] op_sel_hi:[1,0]
	v_pk_mul_f32 v[34:35], v[34:35], v[194:195] op_sel_hi:[1,0]
	v_mul_f32_e32 v170, v170, v192
	v_mul_f32_e32 v171, v171, v193
	v_mov_b32_e32 v192, v193
	v_pk_mul_f32 v[32:33], v[32:33], v[194:195] op_sel_hi:[1,0]
	v_pk_mul_f32 v[14:15], v[14:15], v[192:193] op_sel_hi:[1,0]
	v_pk_mul_f32 v[12:13], v[12:13], v[192:193] op_sel_hi:[1,0]
	v_pk_mul_f32 v[10:11], v[10:11], v[192:193] op_sel_hi:[1,0]
	v_pk_mul_f32 v[8:9], v[8:9], v[192:193] op_sel_hi:[1,0]
	v_pk_mul_f32 v[6:7], v[6:7], v[192:193] op_sel_hi:[1,0]
	v_pk_mul_f32 v[4:5], v[4:5], v[192:193] op_sel_hi:[1,0]
	v_pk_mul_f32 v[2:3], v[2:3], v[192:193] op_sel_hi:[1,0]
	v_pk_mul_f32 v[0:1], v[0:1], v[192:193] op_sel_hi:[1,0]
	v_mov_b32_e32 v167, v161
	v_mov_b32_e32 v192, v195
	v_mov_b32_e32 v193, v196
	v_mov_b32_e32 v194, v197
	s_branch .LBB0_598

; template <int MODE  , int QLO, int QHI> ...
;     ...
;             const int TA = jtA - (j0 + 16 * qt), TB = TA + 16;
;             const bool rA = vA && TA >= -256 && TA <= 256, rB = vB && TB >= -256 && TB <= 256;
;             const int ixA = (TA + 256) >> 4;
;             cA[qt] = cfar[(rA ? ixA : 33) * 64 + lane]; cB[qt] = cfar[(rB ? ixA + 1 : 33) * 64 + lane];
;             vsA[qt] = L.s0 ? sA[qt][0] : (L.s1 ? sA[qt][1] : (L.s2 ? sA[qt][2] : sA[qt][3]));
;             vsB[qt] = L.s0 ? sB[qt][0] : (L.s1 ? sB[qt][1] : (L.s2 ? sB[qt][2] : sB[qt][3]));
;             tmax[qt] = xmax16_32(fmaxf(vsA[qt], vsB[qt]));
;         }
;         bool need = false;
; #pragma unroll
;         for (int qt = QLO; qt < QHI; ++qt) need = need || (tmax[qt] > mrun[qt] + 8.f);
;         if (__builtin_amdgcn_ballot_w64(need) != 0ull) {
; #pragma unroll
;             for (int qt = QLO; qt < QHI; ++qt) {
;                 const float mnew = fmaxf(mrun[qt], tmax[qt]); const float alpha = __builtin_amdgcn_exp2f(mrun[qt] - mnew);
;                 mrun[qt] = mnew; lrun[qt] *= alpha;
; #pragma unroll
;                 for (int dt = 0; dt < 4; ++dt) O[qt][dt] = O[qt][dt] * alpha;
;             }
;         }
.LBB0_634:
	s_cmp_lt_u32 s66, 21
	s_cselect_b32 s0, -15, -9
	s_add_i32 s58, s0, s66
	s_lshl_b32 s64, s58, 5
	s_add_i32 s0, s64, s80
	s_cmpk_lt_u32 s0, 0x800
	s_cselect_b64 s[42:43], -1, 0
	s_sub_i32 s14, s0, s79
	s_add_i32 s0, s14, 0x100
	s_cmpk_lt_u32 s0, 0x201
	s_cselect_b64 s[0:1], -1, 0
	s_and_b64 s[0:1], s[42:43], s[0:1]
	s_add_i32 s4, s14, 0x110
	s_cmpk_lt_u32 s4, 0x201
	s_cselect_b64 s[4:5], -1, 0
	s_lshl_b32 s14, s14, 2
	s_and_b64 s[4:5], s[42:43], s[4:5]
	s_add_i32 s15, s14, 0x400
	s_and_b64 s[0:1], s[0:1], exec
	s_cselect_b32 s0, s15, 0x840
	s_addk_i32 s14, 0x440
	v_lshl_add_u32 v161, s0, 2, v190
	s_and_b64 s[0:1], s[4:5], exec
	s_cselect_b32 s0, s14, 0x840
	v_cmp_eq_u32_e32 vcc, 1, v162
	v_lshl_add_u32 v195, s0, 2, v190
	v_cmp_eq_u32_e64 s[0:1], 2, v162
	v_cndmask_b32_e32 v156, v156, v157, vcc
	v_cndmask_b32_e32 v152, v152, v153, vcc
	v_cndmask_b32_e64 v156, v156, v158, s[0:1]
	v_cmp_eq_u32_e64 s[4:5], 3, v162
	v_cndmask_b32_e64 v152, v152, v154, s[0:1]
	s_add_i32 s14, s64, -16
	v_cndmask_b32_e64 v156, v156, v159, s[4:5]
	v_cndmask_b32_e64 v152, v152, v155, s[4:5]
	v_max_f32_e32 v153, v156, v152
	s_cmpk_lt_u32 s14, 0x201
	s_cselect_b64 s[14:15], -1, 0
	s_and_b64 s[14:15], s[42:43], s[14:15]
	s_cmp_lt_u32 s58, 17
	s_cselect_b64 s[48:49], -1, 0
	s_lshl_b32 s58, s58, 7
	s_and_b64 s[48:49], s[48:49], s[42:43]
	s_sub_i32 s65, s58, 64
	s_and_b64 s[14:15], s[14:15], exec
	s_cselect_b32 s14, s65, 0x840
	v_lshl_add_u32 v154, s14, 2, v190
	s_and_b64 s[14:15], s[48:49], exec
	s_cselect_b32 s14, s58, 0x840
	v_lshl_add_u32 v155, s14, 2, v190
	s_sub_i32 s14, s64, 32
	v_cndmask_b32_e32 v148, v148, v149, vcc
	v_cndmask_b32_e32 v144, v144, v145, vcc
	s_cmpk_lt_u32 s14, 0x201
	v_cndmask_b32_e32 v140, v140, v141, vcc
	v_cndmask_b32_e32 v136, v136, v137, vcc
	v_cndmask_b32_e64 v148, v148, v150, s[0:1]
	v_cndmask_b32_e64 v144, v144, v146, s[0:1]
	s_cselect_b64 s[14:15], -1, 0
	v_cndmask_b32_e64 v140, v140, v142, s[0:1]
	v_cndmask_b32_e64 v136, v136, v138, s[0:1]
	v_cndmask_b32_e64 v148, v148, v151, s[4:5]
	v_cndmask_b32_e64 v144, v144, v147, s[4:5]
	s_and_b64 s[14:15], s[42:43], s[14:15]
	s_add_i32 s48, s58, 0xffffff80
	v_cndmask_b32_e64 v142, v140, v143, s[4:5]
	v_cndmask_b32_e64 v143, v136, v139, s[4:5]
	s_and_b64 s[14:15], s[14:15], exec
	v_cndmask_b32_e32 v128, v128, v129, vcc
	v_cndmask_b32_e32 v129, v132, v133, vcc
	v_max_f32_e32 v146, v148, v144
	s_cselect_b32 s14, s48, 0x840
	v_max_f32_e32 v145, v142, v143
	v_cndmask_b32_e64 v128, v128, v130, s[0:1]
	v_cndmask_b32_e64 v129, v129, v134, s[0:1]
	v_lshl_add_u32 v147, s14, 2, v190
	s_sub_i32 s14, s64, 48
	v_cndmask_b32_e64 v128, v128, v131, s[4:5]
	v_cndmask_b32_e64 v129, v129, v135, s[4:5]
	s_cmpk_lt_u32 s14, 0x201
	s_cselect_b64 s[14:15], -1, 0
	v_max_f32_e32 v130, v128, v129
	s_and_b64 s[14:15], s[42:43], s[14:15]
	s_addk_i32 s58, 0xff40
	s_and_b64 s[14:15], s[14:15], exec
	s_cselect_b32 s14, s58, 0x840
	v_lshl_add_u32 v139, s14, 2, v190
	ds_read_b32 v136, v161
	ds_read_b32 v140, v195
	ds_read_b32 v137, v154
	ds_read_b32 v141, v155
	ds_read_b32 v138, v147
	ds_read_b32 v139, v139
	v_add_f32_e32 v131, 0x41000000, v194
	v_cmp_gt_f32_e32 vcc, v153, v131
	v_add_f32_e32 v131, 0x41000000, v193
	v_cmp_gt_f32_e64 s[0:1], v146, v131
	v_add_f32_e32 v131, 0x41000000, v192
	s_or_b64 s[0:1], vcc, s[0:1]
	v_cmp_gt_f32_e32 vcc, v145, v131
	v_add_f32_e32 v131, 0x41000000, v167
	s_or_b64 s[0:1], s[0:1], vcc
	v_cmp_gt_f32_e32 vcc, v130, v131
	s_or_b64 vcc, s[0:1], vcc
	s_cbranch_vccz .LBB0_636
	v_mov_b32_e32 v131, v153
	s_nop 1
	v_permlane16_swap_b32_e32 v153, v131
	v_max_f32_e32 v153, v153, v131
	v_mov_b32_e32 v131, v153
	s_nop 1
	v_permlane32_swap_b32_e32 v153, v131
	v_max_f32_e32 v153, v153, v131
	v_mov_b32_e32 v131, v146
	s_nop 1
	v_permlane16_swap_b32_e32 v146, v131
	v_max_f32_e32 v146, v146, v131
	v_mov_b32_e32 v131, v146
	s_nop 1
	v_permlane32_swap_b32_e32 v146, v131
	v_max_f32_e32 v146, v146, v131
	v_mov_b32_e32 v131, v145
	s_nop 1
	v_permlane16_swap_b32_e32 v145, v131
	v_max_f32_e32 v145, v145, v131
	v_mov_b32_e32 v131, v145
	s_nop 1
	v_permlane32_swap_b32_e32 v145, v131
	v_max_f32_e32 v145, v145, v131
	v_mov_b32_e32 v131, v130
	s_nop 1
	v_permlane16_swap_b32_e32 v130, v131
	v_max_f32_e32 v130, v130, v131
	v_mov_b32_e32 v131, v130
	s_nop 1
	v_permlane32_swap_b32_e32 v130, v131
	v_max_f32_e32 v130, v130, v131
	v_max_f32_e32 v131, v153, v153
	v_max_f32_e32 v132, v194, v194
	v_max_f32_e32 v131, v132, v131
	v_sub_f32_e32 v132, v194, v131
	v_exp_f32_e32 v132, v132
	v_max_f32_e32 v134, v193, v193
	v_max_f32_e32 v130, v130, v130
	v_mov_b32_e32 v194, v131
	v_pk_mul_f32 v[62:63], v[62:63], v[132:133] op_sel_hi:[1,0]
	v_pk_mul_f32 v[60:61], v[60:61], v[132:133] op_sel_hi:[1,0]
	v_pk_mul_f32 v[58:59], v[58:59], v[132:133] op_sel_hi:[1,0]
	v_pk_mul_f32 v[56:57], v[56:57], v[132:133] op_sel_hi:[1,0]
	v_pk_mul_f32 v[54:55], v[54:55], v[132:133] op_sel_hi:[1,0]
	v_pk_mul_f32 v[52:53], v[52:53], v[132:133] op_sel_hi:[1,0]
	v_pk_mul_f32 v[50:51], v[50:51], v[132:133] op_sel_hi:[1,0]
	v_pk_mul_f32 v[48:49], v[48:49], v[132:133] op_sel_hi:[1,0]
	v_max_f32_e32 v133, v146, v146
	v_max_f32_e32 v146, v134, v133
	v_sub_f32_e32 v133, v193, v146
	v_exp_f32_e32 v133, v133
	v_max_f32_e32 v134, v192, v192
	v_mov_b32_e32 v193, v146
	v_mul_f32_e32 v178, v178, v132
	v_mul_f32_e32 v179, v179, v133
	v_mov_b32_e32 v132, v133
	v_pk_mul_f32 v[46:47], v[46:47], v[132:133] op_sel_hi:[1,0]
	v_pk_mul_f32 v[44:45], v[44:45], v[132:133] op_sel_hi:[1,0]
	v_max_f32_e32 v133, v145, v145
	v_max_f32_e32 v133, v134, v133
	v_sub_f32_e32 v134, v192, v133
	v_exp_f32_e32 v134, v134
	v_pk_mul_f32 v[42:43], v[42:43], v[132:133] op_sel_hi:[1,0]
; __device__ __forceinline__ unsigned cvt_pk_bf16(float lo, float hi) { unsigned r; asm volatile("v_cvt_pk_bf16_f32 %0, %1, %2" : "=v"(r) : "v"(lo), "v"(hi)); return r; }
; template <int MODE  , int QLO, int QHI> ...
;     ...
;             for (int qt = QLO; qt < QHI; ++qt) {
;                 const float mnew = fmaxf(mrun[qt], tmax[qt]); const float alpha = __builtin_amdgcn_exp2f(mrun[qt] - mnew);
;                 mrun[qt] = mnew; lrun[qt] *= alpha;
; #pragma unroll
;                 for (int dt = 0; dt < 4; ++dt) O[qt][dt] = O[qt][dt] * alpha;
;             }
;         }
; #pragma unroll
;         for (int qt = QLO; qt < QHI; ++qt) {
;             const float pA = cA[qt] * __builtin_amdgcn_exp2f(vsA[qt] - mrun[qt]), pB = cB[qt] * __builtin_amdgcn_exp2f(vsB[qt] - mrun[qt]);
;             lrun[qt] += pA + pB;
;             const unsigned wA = pg8::cvt_pk_bf16(pA, pA), wB = pg8::cvt_pk_bf16(pB, pB);
;             const u32x4 pw = (u32x4){wA & L.mx, wA & L.my, wB & L.mx, wB & L.my};
;             const bf16x8 P = __builtin_bit_cast(bf16x8, pw);
; #pragma unroll
;             for (int dt = 0; dt < 4; ++dt) O[qt][dt] = __builtin_amdgcn_mfma_f32_16x16x32_bf16(Vf[dt], P, O[qt][dt], 0, 0, 0);
;         }
	v_pk_mul_f32 v[40:41], v[40:41], v[132:133] op_sel_hi:[1,0]
	v_pk_mul_f32 v[38:39], v[38:39], v[132:133] op_sel_hi:[1,0]
	v_pk_mul_f32 v[30:31], v[30:31], v[134:135] op_sel_hi:[1,0]
	v_pk_mul_f32 v[28:29], v[28:29], v[134:135] op_sel_hi:[1,0]
	v_pk_mul_f32 v[26:27], v[26:27], v[134:135] op_sel_hi:[1,0]
	v_pk_mul_f32 v[24:25], v[24:25], v[134:135] op_sel_hi:[1,0]
	v_pk_mul_f32 v[22:23], v[22:23], v[134:135] op_sel_hi:[1,0]
	v_pk_mul_f32 v[20:21], v[20:21], v[134:135] op_sel_hi:[1,0]
	v_pk_mul_f32 v[18:19], v[18:19], v[134:135] op_sel_hi:[1,0]
	v_pk_mul_f32 v[16:17], v[16:17], v[134:135] op_sel_hi:[1,0]
	v_max_f32_e32 v135, v167, v167
	v_max_f32_e32 v145, v135, v130
	v_sub_f32_e32 v130, v167, v145
	v_exp_f32_e32 v135, v130
	v_pk_mul_f32 v[36:37], v[36:37], v[132:133] op_sel_hi:[1,0]
	v_pk_mul_f32 v[34:35], v[34:35], v[132:133] op_sel_hi:[1,0]
	v_pk_mul_f32 v[32:33], v[32:33], v[132:133] op_sel_hi:[1,0]
	v_mov_b32_e32 v130, v135
	v_mul_f32_e32 v170, v170, v134
	v_mul_f32_e32 v171, v171, v135
	v_pk_mul_f32 v[14:15], v[14:15], v[130:131] op_sel_hi:[1,0]
	v_pk_mul_f32 v[12:13], v[12:13], v[130:131] op_sel_hi:[1,0]
	v_pk_mul_f32 v[10:11], v[10:11], v[130:131] op_sel_hi:[1,0]
	v_pk_mul_f32 v[8:9], v[8:9], v[130:131] op_sel_hi:[1,0]
	v_pk_mul_f32 v[6:7], v[6:7], v[130:131] op_sel_hi:[1,0]
	v_pk_mul_f32 v[4:5], v[4:5], v[130:131] op_sel_hi:[1,0]
	v_pk_mul_f32 v[2:3], v[2:3], v[130:131] op_sel_hi:[1,0]
	v_pk_mul_f32 v[0:1], v[0:1], v[130:131] op_sel_hi:[1,0]
	v_mov_b32_e32 v167, v145
	v_mov_b32_e32 v192, v133
.LBB0_636:
	v_sub_f32_e32 v130, v156, v194
	v_sub_f32_e32 v131, v148, v193
	v_exp_f32_e32 v134, v130
	v_sub_f32_e32 v130, v152, v194
	v_exp_f32_e32 v135, v131
	v_sub_f32_e32 v131, v144, v193
	v_exp_f32_e32 v130, v130
	v_exp_f32_e32 v131, v131
	s_waitcnt lgkmcnt(3)
	v_mul_f32_e32 v144, v136, v134
	v_mul_f32_e32 v145, v137, v135
	v_sub_f32_e32 v142, v142, v192
	v_sub_f32_e32 v128, v128, v167
	s_waitcnt lgkmcnt(2)
	v_mul_f32_e32 v140, v140, v130
	v_mul_f32_e32 v141, v141, v131
	v_cvt_pk_bf16_f32 v131, v144, v144
	v_sub_f32_e32 v129, v129, v167
	v_cvt_pk_bf16_f32 v133, v140, v140
	v_and_b32_e32 v130, v131, v183
	v_and_b32_e32 v131, v131, v189
	v_and_b32_e32 v132, v133, v183
	v_and_b32_e32 v133, v133, v189
	v_exp_f32_e32 v129, v129
	s_xor_b32 s83, s83, 1
	v_mfma_f32_16x16x32_bf16 v[60:63], v[124:127], v[130:133], v[60:63]
	s_cmp_gt_u32 s33, 26
	v_mfma_f32_16x16x32_bf16 v[56:59], v[120:123], v[130:133], v[56:59]
	v_mfma_f32_16x16x32_bf16 v[52:55], v[116:119], v[130:133], v[52:55]
	v_mfma_f32_16x16x32_bf16 v[48:51], v[112:115], v[130:133], v[48:51]
	v_cvt_pk_bf16_f32 v131, v145, v145
	v_cvt_pk_bf16_f32 v133, v141, v141
	s_nop 0
	v_and_b32_e32 v130, v131, v183
	v_and_b32_e32 v131, v131, v189
	v_and_b32_e32 v132, v133, v183
	v_and_b32_e32 v133, v133, v189
	s_nop 1
	v_mfma_f32_16x16x32_bf16 v[44:47], v[124:127], v[130:133], v[44:47]
	v_mfma_f32_16x16x32_bf16 v[40:43], v[120:123], v[130:133], v[40:43]
	v_mfma_f32_16x16x32_bf16 v[36:39], v[116:119], v[130:133], v[36:39]
	v_mfma_f32_16x16x32_bf16 v[32:35], v[112:115], v[130:133], v[32:35]
	v_sub_f32_e32 v130, v143, v192
	v_exp_f32_e32 v132, v142
	v_exp_f32_e32 v133, v128
	v_exp_f32_e32 v128, v130
	v_mov_b32_e32 v130, v137
	s_waitcnt lgkmcnt(1)
	v_mov_b32_e32 v131, v138
	s_waitcnt lgkmcnt(0)
	v_mul_f32_e32 v142, v138, v132
	v_mul_f32_e32 v143, v139, v133
	v_mul_f32_e32 v144, v130, v128
	v_mul_f32_e32 v145, v131, v129
	v_cvt_pk_bf16_f32 v129, v142, v142
	s_nop 0
	v_cvt_pk_bf16_f32 v131, v144, v144
	v_and_b32_e32 v128, v129, v183
	v_and_b32_e32 v129, v129, v189
	v_and_b32_e32 v130, v131, v183
	v_and_b32_e32 v131, v131, v189
	s_nop 1
	v_mfma_f32_16x16x32_bf16 v[28:31], v[124:127], v[128:131], v[28:31]
	v_mfma_f32_16x16x32_bf16 v[24:27], v[120:123], v[128:131], v[24:27]
	v_mfma_f32_16x16x32_bf16 v[20:23], v[116:119], v[128:131], v[20:23]
	v_mfma_f32_16x16x32_bf16 v[16:19], v[112:115], v[128:131], v[16:19]
	v_cvt_pk_bf16_f32 v129, v143, v143
	v_cvt_pk_bf16_f32 v131, v145, v145
	s_nop 0
	v_and_b32_e32 v128, v129, v183
	v_and_b32_e32 v129, v129, v189
	v_and_b32_e32 v130, v131, v183
	v_and_b32_e32 v131, v131, v189
	s_nop 1
	v_mfma_f32_16x16x32_bf16 v[12:15], v[124:127], v[128:131], v[12:15]
	v_mfma_f32_16x16x32_bf16 v[8:11], v[120:123], v[128:131], v[8:11]
	v_fma_f32 v120, v136, v134, v140
	v_fma_f32 v121, v137, v135, v141
	v_add_f32_e32 v178, v178, v120
	v_add_f32_e32 v179, v179, v121
	v_mfma_f32_16x16x32_bf16 v[4:7], v[116:119], v[128:131], v[4:7]
	v_fma_f32 v116, v138, v132, v144
	v_fma_f32 v117, v139, v133, v145
	v_add_f32_e32 v170, v170, v116
	v_add_f32_e32 v171, v171, v117
	v_mfma_f32_16x16x32_bf16 v[0:3], v[112:115], v[128:131], v[0:3]
	s_cbranch_scc1 .LBB0_712
	s_mov_b32 s66, s33
	s_branch .LBB0_605
; __device__ __forceinline__ u32x4 pack8(f32x4 a, f32x4 b) { u32x4 w; w.x = cvt_pk_bf16(a[0], a[1]); w.y = cvt_pk_bf16(a[2], a[3]); w.z = cvt_pk_bf16(b[0], b[1]); w.w = cvt_pk_bf16(b[2], b[3]); return w; }
; template <int MODE  , int QLO, int QHI> ...
;     ...
; #pragma unroll
;         for (int qt = QLO; qt < QHI; ++qt) {
;             const int TA = jtA - (j0 + 16 * qt), TB = TA + 16;
;             const bool rA = vA && (same ? (TA >= -256 && TA <= 256) : (TA >= -16 && TA <= 16));
;             const bool rB = vB && (same ? (TB >= -256 && TB <= 256) : (TB >= -16 && TB <= 16));
;             const int ixA = same ? ((TA + 256) >> 4) : (33 + (dr + 3) * 3 + ((TA + 16) >> 4));
;             const f32x4 cAq = ctf[(rA ? ixA : 54) * 64 + lane], cBq = ctf[(rB ? ixA + 1 : 54) * 64 + lane];
;             const f32x4 dA = sA[qt] - mrun[qt], dB = sB[qt] - mrun[qt];
;             f32x4 eA, eB;
; #pragma unroll
;             for (int r = 0; r < 4; ++r) { eA[r] = __builtin_amdgcn_exp2f(dA[r]); eB[r] = __builtin_amdgcn_exp2f(dB[r]); }
;             const f32x4 pA = cAq * eA, pB = cBq * eB;
;             const f32x4 sm = pA + pB;
;             lrun[qt] += (sm[0] + sm[1]) + (sm[2] + sm[3]);
;             const bf16x8 P = __builtin_bit_cast(bf16x8, pg8::pack8(pA, pB));
; #pragma unroll
;             for (int dt = 0; dt < 4; ++dt) O[qt][dt] = __builtin_amdgcn_mfma_f32_16x16x32_bf16(Vf[dt], P, O[qt][dt], 0, 0, 0);
;         }
.LBB0_638:
	s_addk_i32 s49, 0xd0
	s_lshr_b32 s0, s71, 4
	s_xor_b32 s83, s83, 1
	s_lshr_b32 s14, s49, 4
	s_add_i32 s15, s0, s48
	s_and_b64 s[0:1], exec, s[4:5]
	s_cselect_b32 s0, s14, s15
	s_lshl_b32 s4, s0, 6
	s_and_b64 s[0:1], s[64:65], exec
	v_add_f32_e32 v136, v136, v140
	v_add_f32_e32 v137, v137, v141
	s_cselect_b32 s0, s4, 0xd80
	s_add_i32 s4, s4, 64
	v_add_f32_e32 v149, v136, v137
	v_lshl_add_u32 v136, s0, 4, v188
	s_and_b64 s[0:1], s[66:67], exec
	s_cselect_b32 s0, s4, 0xd80
	v_add_f32_e32 v138, v138, v142
	v_add_f32_e32 v139, v139, v143
	v_lshl_add_u32 v140, s0, 4, v188
	v_sub_f32_e32 v128, v128, v167
	v_sub_f32_e32 v129, v129, v167
	v_sub_f32_e32 v130, v130, v167
	v_sub_f32_e32 v131, v131, v167
	v_add_f32_e32 v148, v138, v139
	ds_read_b128 v[136:139], v136
	ds_read_b128 v[140:143], v140
	v_exp_f32_e32 v144, v128
	v_sub_f32_e32 v128, v132, v167
	v_exp_f32_e32 v145, v129
	v_sub_f32_e32 v129, v133, v167
	v_exp_f32_e32 v132, v130
	v_sub_f32_e32 v130, v134, v167
	v_exp_f32_e32 v133, v131
	v_sub_f32_e32 v131, v135, v167
	v_exp_f32_e32 v128, v128
	v_exp_f32_e32 v129, v129
	v_exp_f32_e32 v130, v130
	v_exp_f32_e32 v131, v131
	s_waitcnt lgkmcnt(1)
	v_mul_f32_e32 v134, v132, v138
	v_mul_f32_e32 v135, v133, v139
	v_mul_f32_e32 v146, v144, v136
	v_mul_f32_e32 v147, v145, v137
	s_waitcnt lgkmcnt(0)
	v_mul_f32_e32 v140, v128, v140
	v_mul_f32_e32 v141, v129, v141
	v_mul_f32_e32 v142, v130, v142
	v_mul_f32_e32 v143, v131, v143
	v_cvt_pk_bf16_f32 v128, v146, v147
	v_cvt_pk_bf16_f32 v129, v134, v135
	v_cvt_pk_bf16_f32 v130, v140, v141
	s_cmp_gt_i32 s33, 14
	v_cvt_pk_bf16_f32 v131, v142, v143
	s_mov_b32 s66, s33
	v_mfma_f32_16x16x32_bf16 v[12:15], v[124:127], v[128:131], v[12:15]
	v_add_f32_e32 v124, v148, v149
	v_add_f32_e32 v126, v170, v124
	v_fma_f32 v124, v132, v138, v142
	v_fma_f32 v125, v133, v139, v143
	v_mfma_f32_16x16x32_bf16 v[8:11], v[120:123], v[128:131], v[8:11]
	v_fma_f32 v120, v144, v136, v140
	v_fma_f32 v121, v145, v137, v141
	v_pk_mov_b32 v[122:123], v[120:121], v[124:125] op_sel:[1,0]
	v_mov_b32_e32 v121, v125
	v_mfma_f32_16x16x32_bf16 v[4:7], v[116:119], v[128:131], v[4:7]
	v_add_f32_e64 v116, v122, v120
	v_add_f32_e64 v117, v123, v121
	v_add_f32_e32 v116, v116, v117
	v_mfma_f32_16x16x32_bf16 v[0:3], v[112:115], v[128:131], v[0:3]
	v_add_f32_e64 v170, v170, v116
	v_add_f32_e64 v171, v171, v116
	v_mov_b32_e32 v170, v126
	s_cbranch_scc1 .LBB0_604

; template <int MODE  , int QLO, int QHI> ...
;     ...
;         float tmax[4];
; #pragma unroll
;         for (int qt = QLO; qt < QHI; ++qt) {
;             const float a = fmaxf(fmaxf(fmaxf(sA[qt][0], sA[qt][1]), fmaxf(sA[qt][2], sA[qt][3])), fmaxf(fmaxf(sB[qt][0], sB[qt][1]), fmaxf(sB[qt][2], sB[qt][3])));
;             tmax[qt] = xmax16_32(a);
;         }
;         bool need = false;
; #pragma unroll
;         for (int qt = QLO; qt < QHI; ++qt) need = need || (tmax[qt] > mrun[qt] + 8.f);
;         if (__builtin_amdgcn_ballot_w64(need) != 0ull) {
; #pragma unroll
;             for (int qt = QLO; qt < QHI; ++qt) {
;                 const float mnew = fmaxf(mrun[qt], tmax[qt]); const float alpha = __builtin_amdgcn_exp2f(mrun[qt] - mnew);
;                 mrun[qt] = mnew; lrun[qt] *= alpha;
; #pragma unroll
;                 for (int dt = 0; dt < 4; ++dt) O[qt][dt] = O[qt][dt] * alpha;
;             }
;         }
.LBB0_690:
	s_nop 1
	v_max3_f32 v144, v136, v137, v138
	v_max3_f32 v145, v139, v140, v141
	v_max3_f32 v144, v144, v142, v143
	v_max_f32_e32 v145, v144, v145
	v_max3_f32 v144, v128, v129, v130
	v_max3_f32 v146, v131, v132, v133
	v_max3_f32 v144, v144, v134, v135
	v_max_f32_e32 v144, v144, v146
	v_add_f32_e32 v146, 0x41000000, v192
	v_cmp_gt_f32_e32 vcc, v145, v146
	v_add_f32_e32 v146, 0x41000000, v167
	v_cmp_gt_f32_e64 s[0:1], v144, v146
	s_or_b64 vcc, vcc, s[0:1]
	s_cbranch_vccz .LBB0_692
	v_mov_b32_e32 v146, v145
	s_nop 1
	v_permlane16_swap_b32_e32 v145, v146
	v_max_f32_e32 v145, v145, v146
	v_mov_b32_e32 v146, v145
	s_nop 1
	v_permlane32_swap_b32_e32 v145, v146
	v_max_f32_e32 v145, v145, v146
	v_mov_b32_e32 v146, v144
	s_nop 1
	v_permlane16_swap_b32_e32 v144, v146
	v_max_f32_e32 v144, v144, v146
	v_mov_b32_e32 v146, v144
	s_nop 1
	v_permlane32_swap_b32_e32 v144, v146
	v_max_f32_e32 v144, v144, v146
	v_max_f32_e32 v145, v145, v145
	v_max_f32_e32 v146, v192, v192
	v_max_f32_e32 v145, v146, v145
	v_sub_f32_e32 v146, v192, v145
	v_exp_f32_e32 v146, v146
	v_max_f32_e32 v144, v144, v144
	v_mov_b32_e32 v192, v145
	v_pk_mul_f32 v[30:31], v[30:31], v[146:147] op_sel_hi:[1,0]
	v_pk_mul_f32 v[28:29], v[28:29], v[146:147] op_sel_hi:[1,0]
	v_pk_mul_f32 v[26:27], v[26:27], v[146:147] op_sel_hi:[1,0]
	v_pk_mul_f32 v[24:25], v[24:25], v[146:147] op_sel_hi:[1,0]
	v_pk_mul_f32 v[22:23], v[22:23], v[146:147] op_sel_hi:[1,0]
	v_pk_mul_f32 v[20:21], v[20:21], v[146:147] op_sel_hi:[1,0]
	v_pk_mul_f32 v[18:19], v[18:19], v[146:147] op_sel_hi:[1,0]
	v_pk_mul_f32 v[16:17], v[16:17], v[146:147] op_sel_hi:[1,0]
	v_max_f32_e32 v147, v167, v167
	v_max_f32_e32 v148, v147, v144
	v_sub_f32_e32 v144, v167, v148
	v_exp_f32_e32 v147, v144
	v_mov_b32_e32 v167, v148
	v_mov_b32_e32 v144, v147
	v_mul_f32_e32 v170, v170, v146
	v_mul_f32_e32 v171, v171, v147
	v_pk_mul_f32 v[14:15], v[14:15], v[144:145] op_sel_hi:[1,0]
	v_pk_mul_f32 v[12:13], v[12:13], v[144:145] op_sel_hi:[1,0]
	v_pk_mul_f32 v[10:11], v[10:11], v[144:145] op_sel_hi:[1,0]
	v_pk_mul_f32 v[8:9], v[8:9], v[144:145] op_sel_hi:[1,0]
	v_pk_mul_f32 v[6:7], v[6:7], v[144:145] op_sel_hi:[1,0]
	v_pk_mul_f32 v[4:5], v[4:5], v[144:145] op_sel_hi:[1,0]
	v_pk_mul_f32 v[2:3], v[2:3], v[144:145] op_sel_hi:[1,0]
	v_pk_mul_f32 v[0:1], v[0:1], v[144:145] op_sel_hi:[1,0]

; __device__ __forceinline__ u32x4 pack8(f32x4 a, f32x4 b) { u32x4 w; w.x = cvt_pk_bf16(a[0], a[1]); w.y = cvt_pk_bf16(a[2], a[3]); w.z = cvt_pk_bf16(b[0], b[1]); w.w = cvt_pk_bf16(b[2], b[3]); return w; }
; template <int MODE  , int QLO, int QHI> ...
;     ...
; #pragma unroll
;         for (int qt = QLO; qt < QHI; ++qt) {
;             const int TA = jtA - (j0 + 16 * qt), TB = TA + 16;
;             const bool rA = vA && (same ? (TA >= -256 && TA <= 256) : (TA >= -16 && TA <= 16));
;             const bool rB = vB && (same ? (TB >= -256 && TB <= 256) : (TB >= -16 && TB <= 16));
;             const int ixA = same ? ((TA + 256) >> 4) : (33 + (dr + 3) * 3 + ((TA + 16) >> 4));
;             const f32x4 cAq = ctf[(rA ? ixA : 54) * 64 + lane], cBq = ctf[(rB ? ixA + 1 : 54) * 64 + lane];
;             const f32x4 dA = sA[qt] - mrun[qt], dB = sB[qt] - mrun[qt];
;             f32x4 eA, eB;
; #pragma unroll
;             for (int r = 0; r < 4; ++r) { eA[r] = __builtin_amdgcn_exp2f(dA[r]); eB[r] = __builtin_amdgcn_exp2f(dB[r]); }
;             const f32x4 pA = cAq * eA, pB = cBq * eB;
;             const f32x4 sm = pA + pB;
;             lrun[qt] += (sm[0] + sm[1]) + (sm[2] + sm[3]);
;             const bf16x8 P = __builtin_bit_cast(bf16x8, pg8::pack8(pA, pB));
; #pragma unroll
;             for (int dt = 0; dt < 4; ++dt) O[qt][dt] = __builtin_amdgcn_mfma_f32_16x16x32_bf16(Vf[dt], P, O[qt][dt], 0, 0, 0);
;         }
.LBB0_702:
	s_sub_i32 s14, s48, s75
	s_mul_i32 s48, s14, 3
	s_add_i32 s48, s48, 42
	s_add_i32 s70, s49, 0xe0
	s_lshr_b32 s14, s84, 4
	s_lshr_b32 s58, s70, 4
	s_add_i32 s71, s14, s48
	s_and_b64 s[14:15], exec, s[4:5]
	s_cselect_b32 s14, s58, s71
	s_lshl_b32 s58, s14, 6
	s_and_b64 s[14:15], s[68:69], exec
	s_cselect_b32 s14, s58, 0xd80
	s_add_i32 s58, s58, 64
	v_lshl_add_u32 v144, s14, 4, v188
	s_and_b64 s[14:15], s[66:67], exec
	v_sub_f32_e32 v136, v136, v192
	s_cselect_b32 s14, s58, 0xd80
	v_exp_f32_e32 v152, v136
	v_sub_f32_e32 v136, v140, v192
	v_lshl_add_u32 v148, s14, 4, v188
	v_exp_f32_e32 v154, v136
	v_sub_f32_e32 v136, v137, v192
	v_sub_f32_e32 v137, v142, v192
	ds_read_b128 v[144:147], v144
	ds_read_b128 v[148:151], v148
	v_exp_f32_e32 v153, v136
	v_sub_f32_e32 v155, v141, v192
	v_sub_f32_e32 v136, v138, v192
	v_exp_f32_e32 v140, v137
	v_sub_f32_e32 v137, v139, v192
	v_sub_f32_e32 v138, v143, v192
	v_exp_f32_e32 v136, v136
	v_exp_f32_e32 v137, v137
	v_exp_f32_e32 v141, v138
	v_exp_f32_e32 v155, v155
	s_waitcnt lgkmcnt(1)
	v_mul_f32_e32 v138, v152, v144
	v_mul_f32_e32 v139, v153, v145
	v_mul_f32_e32 v136, v136, v146
	v_mul_f32_e32 v137, v137, v147
	s_waitcnt lgkmcnt(0)
	v_mul_f32_e32 v140, v140, v150
	v_mul_f32_e32 v141, v141, v151
	v_mul_f32_e32 v142, v154, v148
	v_mul_f32_e32 v143, v155, v149
	v_cvt_pk_bf16_f32 v144, v138, v139
	v_cvt_pk_bf16_f32 v145, v136, v137
	s_sub_i32 s71, s49, 32
	v_cvt_pk_bf16_f32 v146, v142, v143
	v_cvt_pk_bf16_f32 v147, v140, v141
	s_mov_b64 s[66:67], 0
	v_mfma_f32_16x16x32_bf16 v[28:31], v[124:127], v[144:147], v[28:31]
	s_andn2_b64 vcc, exec, s[0:1]
	v_mfma_f32_16x16x32_bf16 v[24:27], v[120:123], v[144:147], v[24:27]
	v_mfma_f32_16x16x32_bf16 v[20:23], v[116:119], v[144:147], v[20:23]
	v_mfma_f32_16x16x32_bf16 v[16:19], v[112:115], v[144:147], v[16:19]
	v_cndmask_b32_e64 v144, 0, 1, s[64:65]
	v_cmp_ne_u32_e64 s[0:1], 1, v144
	s_mov_b64 s[64:65], 0
	s_cbranch_vccnz .LBB0_707
	s_and_b64 vcc, exec, s[0:1]
	s_mov_b64 s[68:69], -1
	s_cbranch_vccnz .LBB0_705
	s_cmp_lt_u32 s71, 33
	s_mov_b64 s[68:69], 0
	s_cselect_b64 s[64:65], -1, 0
